# W_in and cross-score epilogues: the batched ssq loads are issued at the K-loop exit in front of the ALIGN_EPI barrier
# speedup vs baseline: 1.0051x; 1.0051x over previous
; #define PG8_STAGE(bufoff, gbase, voff) do { _Pragma("unroll") for (int _i = 0; _i < 2; ++_i) \
;         __builtin_amdgcn_global_load_lds((const unsigned*)((const char*)(gbase) + (voff)[_i]), (PG8_LAS unsigned*)(lds + (bufoff) + ldsw + _i * 8192), 16, 0, 0); } while (0)
; #define PG8_LDA(dst, b, h) do { _Pragma("unroll") for (int m = 0; m < 4; ++m) _Pragma("unroll") for (int k = 0; k < 2; ++k) dst[m][k] = *(const PG8_LAS bf16x8*)(lds + PG8_SA(b, h) + aoff + m * 2048 + k * 1024); } while (0)
; #define PG8_LDB(dst, b, h) do { _Pragma("unroll") for (int n = 0; n < 2; ++n) _Pragma("unroll") for (int k = 0; k < 2; ++k) dst[n][k] = *(const PG8_LAS bf16x8*)(lds + PG8_SB(b, h) + boff + n * 2048 + k * 1024); } while (0)
; #define PG8_MMA(ai, bj, At, Bt) do { __builtin_amdgcn_s_setprio(1); _Pragma("unroll") for (int m = 0; m < 4; ++m) _Pragma("unroll") for (int n = 0; n < 2; ++n) _Pragma("unroll") for (int k = 0; k < 2; ++k) \
;         acc[ai][bj][m][n] = __builtin_amdgcn_mfma_f32_16x16x32_bf16(Bt[n][k], At[m][k], acc[ai][bj][m][n], 0, 0, 0); __builtin_amdgcn_s_setprio(0); } while (0)
; #define PG8_WAIT_V(n) asm volatile("s_waitcnt vmcnt(" #n ")" ::: "memory")
; #define PG8_WAIT_L(n) asm volatile("s_waitcnt lgkmcnt(" #n ")" ::: "memory")
; #define PG8_BAR __builtin_amdgcn_s_barrier()
; #define PG8_SCHED __builtin_amdgcn_sched_barrier(0)
; template <class Epi, class Sched, bool ALIGN_EPI = false, bool SP2 = false>
; __device__ __forceinline__ void gemm_phase(PG8_LAS unsigned char* lds, const Gemm g, const Sched& S, const Epi& E) {
;     ...
;             PG8_LDB(B0, 0, 0); PG8_LDB(B1, 0, 1); PG8_SCHED; PG8_LDA(At, 0, 0); PG8_STAGE(PG8_SA(1, 1), a1 + hstepA, voffA);
;             PG8_WAIT_V(8); PG8_WAIT_L(0); PG8_BAR; PG8_MMA(0, 0, At, B0); PG8_MMA(0, 1, At, B1); PG8_BAR; PG8_SCHED;
;             PG8_LDA(At, 0, 1); PG8_STAGE(PG8_SB(0, 0), b2, voffB); PG8_STAGE(PG8_SB(0, 1), b2 + hstepB, voffB); PG8_STAGE(PG8_SA(0, 0), a2, voffA);
;             PG8_WAIT_V(8); PG8_WAIT_L(0); PG8_BAR; PG8_MMA(1, 0, At, B0); PG8_MMA(1, 1, At, B1); PG8_BAR; PG8_SCHED;
;             PG8_LDB(B0, 1, 0); PG8_LDB(B1, 1, 1); PG8_SCHED; PG8_LDA(At, 1, 0); PG8_STAGE(PG8_SA(0, 1), a2 + hstepA, voffA);
;             PG8_WAIT_V(8); PG8_WAIT_L(0); PG8_BAR; PG8_MMA(0, 0, At, B0); PG8_MMA(0, 1, At, B1); PG8_BAR; PG8_SCHED;
.LBB0_380:
	v_add_u32_e32 v140, s85, v173
	v_add_u32_e32 v170, s78, v173
	ds_read_b128 v[128:131], v140
	ds_read_b128 v[132:135], v140 offset:1024
	ds_read_b128 v[136:139], v140 offset:2048
	ds_read_b128 v[140:143], v140 offset:3072
	ds_read_b128 v[144:147], v170
	ds_read_b128 v[148:151], v170 offset:1024
	ds_read_b128 v[166:169], v170 offset:2048
	ds_read_b128 v[176:179], v170 offset:3072
	s_add_u32 s2, s12, 0xfffc0080
	s_addc_u32 s14, s13, -1
	s_cmp_eq_u32 s22, 12
	s_cselect_b32 s17, s9, s14
	s_cselect_b32 s16, s11, s2
	s_cselect_b32 s15, s18, s21
	s_cselect_b32 s14, s19, s20
	v_lshl_add_u64 v[170:171], s[12:13], 0, v[164:165]
	s_add_i32 m0, s61, 0xc000
	ds_read_b128 v[180:183], v175
	ds_read_b128 v[184:187], v175 offset:1024
	ds_read_b128 v[188:191], v175 offset:2048
	ds_read_b128 v[204:207], v175 offset:3072
	ds_read_b128 v[208:211], v175 offset:4096
	ds_read_b128 v[218:221], v175 offset:5120
	ds_read_b128 v[222:225], v175 offset:6144
	ds_read_b128 v[226:229], v175 offset:7168
	global_load_lds_dwordx4 v[170:171], off
	v_lshl_add_u64 v[170:171], s[12:13], 0, v[162:163]
	s_add_i32 m0, s61, 0xe000
	s_nop 0
	global_load_lds_dwordx4 v[170:171], off
	s_waitcnt vmcnt(8)
	s_waitcnt lgkmcnt(0)
	s_barrier
	s_setprio 1
	s_waitcnt lgkmcnt(0)
	v_mfma_f32_16x16x32_bf16 v[60:63], v[128:131], v[180:183], v[60:63]
	v_mfma_f32_16x16x32_bf16 v[56:59], v[136:139], v[180:183], v[56:59]
	v_mfma_f32_16x16x32_bf16 v[52:55], v[128:131], v[188:191], v[52:55]
	v_mfma_f32_16x16x32_bf16 v[48:51], v[136:139], v[188:191], v[48:51]
	v_mfma_f32_16x16x32_bf16 v[44:47], v[128:131], v[208:211], v[44:47]
	v_mfma_f32_16x16x32_bf16 v[40:43], v[136:139], v[208:211], v[40:43]
	v_mfma_f32_16x16x32_bf16 v[36:39], v[128:131], v[222:225], v[36:39]
	v_mfma_f32_16x16x32_bf16 v[32:35], v[136:139], v[222:225], v[32:35]
	v_mfma_f32_16x16x32_bf16 v[60:63], v[132:135], v[184:187], v[60:63]
	v_mfma_f32_16x16x32_bf16 v[56:59], v[140:143], v[184:187], v[56:59]
	v_mfma_f32_16x16x32_bf16 v[52:55], v[132:135], v[204:207], v[52:55]
	v_mfma_f32_16x16x32_bf16 v[48:51], v[140:143], v[204:207], v[48:51]
	v_mfma_f32_16x16x32_bf16 v[44:47], v[132:135], v[218:221], v[44:47]
	v_mfma_f32_16x16x32_bf16 v[40:43], v[140:143], v[218:221], v[40:43]
	v_mfma_f32_16x16x32_bf16 v[36:39], v[132:135], v[226:229], v[36:39]
	v_mfma_f32_16x16x32_bf16 v[32:35], v[140:143], v[226:229], v[32:35]
	s_setprio 0
	s_setprio 1
	v_mfma_f32_16x16x32_bf16 v[124:127], v[144:147], v[180:183], v[124:127]
	v_mfma_f32_16x16x32_bf16 v[120:123], v[166:169], v[180:183], v[120:123]
	v_mfma_f32_16x16x32_bf16 v[116:119], v[144:147], v[188:191], v[116:119]
	v_mfma_f32_16x16x32_bf16 v[112:115], v[166:169], v[188:191], v[112:115]
	v_mfma_f32_16x16x32_bf16 v[108:111], v[144:147], v[208:211], v[108:111]
	v_mfma_f32_16x16x32_bf16 v[104:107], v[166:169], v[208:211], v[104:107]
	v_mfma_f32_16x16x32_bf16 v[100:103], v[144:147], v[222:225], v[100:103]
	v_mfma_f32_16x16x32_bf16 v[96:99], v[166:169], v[222:225], v[96:99]
	v_mfma_f32_16x16x32_bf16 v[124:127], v[148:151], v[184:187], v[124:127]
	v_mfma_f32_16x16x32_bf16 v[120:123], v[176:179], v[184:187], v[120:123]
	v_mfma_f32_16x16x32_bf16 v[116:119], v[148:151], v[204:207], v[116:119]
	v_mfma_f32_16x16x32_bf16 v[112:115], v[176:179], v[204:207], v[112:115]
	v_mfma_f32_16x16x32_bf16 v[108:111], v[148:151], v[218:221], v[108:111]
	v_mfma_f32_16x16x32_bf16 v[104:107], v[176:179], v[218:221], v[104:107]
	v_mfma_f32_16x16x32_bf16 v[100:103], v[148:151], v[226:229], v[100:103]
	v_mfma_f32_16x16x32_bf16 v[96:99], v[176:179], v[226:229], v[96:99]
	s_setprio 0
	s_barrier
	s_mov_b32 m0, s70
	v_lshl_add_u64 v[170:171], s[14:15], 0, v[154:155]
	s_add_u32 s24, s14, 0x40000
	ds_read_b128 v[180:183], v175 offset:16384
	ds_read_b128 v[184:187], v175 offset:17408
	ds_read_b128 v[188:191], v175 offset:18432
	ds_read_b128 v[204:207], v175 offset:19456
	ds_read_b128 v[208:211], v175 offset:20480
	ds_read_b128 v[218:221], v175 offset:21504
	ds_read_b128 v[222:225], v175 offset:22528
	ds_read_b128 v[226:229], v175 offset:23552
	global_load_lds_dwordx4 v[170:171], off
	v_lshl_add_u64 v[230:231], s[14:15], 0, v[158:159]
	s_mov_b32 m0, s71
	s_addc_u32 s25, s15, 0
	global_load_lds_dwordx4 v[230:231], off
	v_lshl_add_u64 v[232:233], s[24:25], 0, v[154:155]
	s_mov_b32 m0, s79
	v_lshl_add_u64 v[234:235], s[16:17], 0, v[156:157]
	global_load_lds_dwordx4 v[232:233], off
	v_lshl_add_u64 v[232:233], s[24:25], 0, v[158:159]
	s_mov_b32 m0, s60
	s_nop 0
	global_load_lds_dwordx4 v[232:233], off
	v_lshl_add_u64 v[232:233], s[16:17], 0, v[152:153]
	s_mov_b32 m0, s61
	s_nop 0
	global_load_lds_dwordx4 v[232:233], off
	s_mov_b32 m0, s75
	s_nop 0
	global_load_lds_dwordx4 v[234:235], off
	s_waitcnt vmcnt(8)
	s_waitcnt lgkmcnt(0)
	s_barrier
; #define PG8_STAGE(bufoff, gbase, voff) do { _Pragma("unroll") for (int _i = 0; _i < 2; ++_i) \
;         __builtin_amdgcn_global_load_lds((const unsigned*)((const char*)(gbase) + (voff)[_i]), (PG8_LAS unsigned*)(lds + (bufoff) + ldsw + _i * 8192), 16, 0, 0); } while (0)
; #define PG8_LDA(dst, b, h) do { _Pragma("unroll") for (int m = 0; m < 4; ++m) _Pragma("unroll") for (int k = 0; k < 2; ++k) dst[m][k] = *(const PG8_LAS bf16x8*)(lds + PG8_SA(b, h) + aoff + m * 2048 + k * 1024); } while (0)
; #define PG8_LDB(dst, b, h) do { _Pragma("unroll") for (int n = 0; n < 2; ++n) _Pragma("unroll") for (int k = 0; k < 2; ++k) dst[n][k] = *(const PG8_LAS bf16x8*)(lds + PG8_SB(b, h) + boff + n * 2048 + k * 1024); } while (0)
; #define PG8_MMA(ai, bj, At, Bt) do { __builtin_amdgcn_s_setprio(1); _Pragma("unroll") for (int m = 0; m < 4; ++m) _Pragma("unroll") for (int n = 0; n < 2; ++n) _Pragma("unroll") for (int k = 0; k < 2; ++k) \
;         acc[ai][bj][m][n] = __builtin_amdgcn_mfma_f32_16x16x32_bf16(Bt[n][k], At[m][k], acc[ai][bj][m][n], 0, 0, 0); __builtin_amdgcn_s_setprio(0); } while (0)
; #define PG8_WAIT_V(n) asm volatile("s_waitcnt vmcnt(" #n ")" ::: "memory")
; #define PG8_WAIT_L(n) asm volatile("s_waitcnt lgkmcnt(" #n ")" ::: "memory")
; #define PG8_BAR __builtin_amdgcn_s_barrier()
; #define PG8_SCHED __builtin_amdgcn_sched_barrier(0)
; template <class Epi, class Sched, bool ALIGN_EPI = false, bool SP2 = false>
; __device__ __forceinline__ void gemm_phase(PG8_LAS unsigned char* lds, const Gemm g, const Sched& S, const Epi& E) {
;     ...
;             PG8_WAIT_V(8); PG8_WAIT_L(0); PG8_BAR; PG8_MMA(1, 0, At, B0); PG8_MMA(1, 1, At, B1); PG8_BAR; PG8_SCHED;
;             PG8_LDB(B0, 1, 0); PG8_LDB(B1, 1, 1); PG8_SCHED; PG8_LDA(At, 1, 0); PG8_STAGE(PG8_SA(0, 1), a2 + hstepA, voffA);
;             PG8_WAIT_V(8); PG8_WAIT_L(0); PG8_BAR; PG8_MMA(0, 0, At, B0); PG8_MMA(0, 1, At, B1); PG8_BAR; PG8_SCHED;
	s_setprio 1
	s_waitcnt lgkmcnt(0)
	v_mfma_f32_16x16x32_bf16 v[28:31], v[128:131], v[180:183], v[28:31]
	v_mfma_f32_16x16x32_bf16 v[24:27], v[136:139], v[180:183], v[24:27]
	v_mfma_f32_16x16x32_bf16 v[20:23], v[128:131], v[188:191], v[20:23]
	v_mfma_f32_16x16x32_bf16 v[16:19], v[136:139], v[188:191], v[16:19]
	v_mfma_f32_16x16x32_bf16 v[12:15], v[128:131], v[208:211], v[12:15]
	v_mfma_f32_16x16x32_bf16 v[8:11], v[136:139], v[208:211], v[8:11]
	v_mfma_f32_16x16x32_bf16 v[4:7], v[128:131], v[222:225], v[4:7]
	v_mfma_f32_16x16x32_bf16 v[0:3], v[136:139], v[222:225], v[0:3]
	v_mfma_f32_16x16x32_bf16 v[28:31], v[132:135], v[184:187], v[28:31]
	v_mfma_f32_16x16x32_bf16 v[24:27], v[140:143], v[184:187], v[24:27]
	v_mfma_f32_16x16x32_bf16 v[20:23], v[132:135], v[204:207], v[20:23]
	v_mfma_f32_16x16x32_bf16 v[16:19], v[140:143], v[204:207], v[16:19]
	v_mfma_f32_16x16x32_bf16 v[12:15], v[132:135], v[218:221], v[12:15]
	v_mfma_f32_16x16x32_bf16 v[8:11], v[140:143], v[218:221], v[8:11]
	v_mfma_f32_16x16x32_bf16 v[4:7], v[132:135], v[226:229], v[4:7]
	v_mfma_f32_16x16x32_bf16 v[0:3], v[140:143], v[226:229], v[0:3]
	s_setprio 0
	s_setprio 1
	v_mfma_f32_16x16x32_bf16 v[92:95], v[144:147], v[180:183], v[92:95]
	v_mfma_f32_16x16x32_bf16 v[88:91], v[166:169], v[180:183], v[88:91]
	v_mfma_f32_16x16x32_bf16 v[84:87], v[144:147], v[188:191], v[84:87]
	v_mfma_f32_16x16x32_bf16 v[80:83], v[166:169], v[188:191], v[80:83]
	v_mfma_f32_16x16x32_bf16 v[76:79], v[144:147], v[208:211], v[76:79]
	v_mfma_f32_16x16x32_bf16 v[72:75], v[166:169], v[208:211], v[72:75]
	v_mfma_f32_16x16x32_bf16 v[68:71], v[144:147], v[222:225], v[68:71]
	v_mfma_f32_16x16x32_bf16 v[64:67], v[166:169], v[222:225], v[64:67]
	v_mfma_f32_16x16x32_bf16 v[92:95], v[148:151], v[184:187], v[92:95]
	v_mfma_f32_16x16x32_bf16 v[88:91], v[176:179], v[184:187], v[88:91]
	v_mfma_f32_16x16x32_bf16 v[84:87], v[148:151], v[204:207], v[84:87]
	v_mfma_f32_16x16x32_bf16 v[80:83], v[176:179], v[204:207], v[80:83]
	v_mfma_f32_16x16x32_bf16 v[76:79], v[148:151], v[218:221], v[76:79]
	v_mfma_f32_16x16x32_bf16 v[72:75], v[176:179], v[218:221], v[72:75]
	v_mfma_f32_16x16x32_bf16 v[68:71], v[148:151], v[226:229], v[68:71]
	v_mfma_f32_16x16x32_bf16 v[64:67], v[176:179], v[226:229], v[64:67]
	s_setprio 0
	s_barrier
	v_add_u32_e32 v140, s68, v173
	v_add_u32_e32 v176, s1, v173
	ds_read_b128 v[128:131], v140
	ds_read_b128 v[132:135], v140 offset:1024
	ds_read_b128 v[136:139], v140 offset:2048
	ds_read_b128 v[140:143], v140 offset:3072
	ds_read_b128 v[144:147], v176
	ds_read_b128 v[148:151], v176 offset:1024
	ds_read_b128 v[166:169], v176 offset:2048
	ds_read_b128 v[176:179], v176 offset:3072
	s_add_u32 s16, s16, 0x40000
	s_addc_u32 s17, s17, 0
	s_mov_b32 m0, s4
	v_lshl_add_u64 v[236:237], s[16:17], 0, v[152:153]
	ds_read_b128 v[180:183], v175 offset:32768
	ds_read_b128 v[184:187], v175 offset:33792
	ds_read_b128 v[188:191], v175 offset:34816
	ds_read_b128 v[204:207], v175 offset:35840
	ds_read_b128 v[208:211], v175 offset:36864
	ds_read_b128 v[218:221], v175 offset:37888
	ds_read_b128 v[222:225], v175 offset:38912
	ds_read_b128 v[226:229], v175 offset:39936
	global_load_lds_dwordx4 v[236:237], off
	v_lshl_add_u64 v[236:237], s[16:17], 0, v[156:157]
	s_mov_b32 m0, s5
	s_nop 0
	global_load_lds_dwordx4 v[236:237], off
	s_waitcnt vmcnt(8)
	s_waitcnt lgkmcnt(0)
	s_barrier
	s_setprio 1
	s_waitcnt lgkmcnt(0)
	v_mfma_f32_16x16x32_bf16 v[60:63], v[128:131], v[180:183], v[60:63]
	v_mfma_f32_16x16x32_bf16 v[56:59], v[136:139], v[180:183], v[56:59]
	v_mfma_f32_16x16x32_bf16 v[52:55], v[128:131], v[188:191], v[52:55]
	v_mfma_f32_16x16x32_bf16 v[48:51], v[136:139], v[188:191], v[48:51]
	v_mfma_f32_16x16x32_bf16 v[44:47], v[128:131], v[208:211], v[44:47]
	v_mfma_f32_16x16x32_bf16 v[40:43], v[136:139], v[208:211], v[40:43]
	v_mfma_f32_16x16x32_bf16 v[36:39], v[128:131], v[222:225], v[36:39]
	v_mfma_f32_16x16x32_bf16 v[32:35], v[136:139], v[222:225], v[32:35]
	v_mfma_f32_16x16x32_bf16 v[60:63], v[132:135], v[184:187], v[60:63]
	v_mfma_f32_16x16x32_bf16 v[56:59], v[140:143], v[184:187], v[56:59]
	v_mfma_f32_16x16x32_bf16 v[52:55], v[132:135], v[204:207], v[52:55]
	v_mfma_f32_16x16x32_bf16 v[48:51], v[140:143], v[204:207], v[48:51]
	v_mfma_f32_16x16x32_bf16 v[44:47], v[132:135], v[218:221], v[44:47]
	v_mfma_f32_16x16x32_bf16 v[40:43], v[140:143], v[218:221], v[40:43]
	v_mfma_f32_16x16x32_bf16 v[36:39], v[132:135], v[226:229], v[36:39]
	v_mfma_f32_16x16x32_bf16 v[32:35], v[140:143], v[226:229], v[32:35]
	s_setprio 0
	s_setprio 1
	v_mfma_f32_16x16x32_bf16 v[124:127], v[144:147], v[180:183], v[124:127]
	v_mfma_f32_16x16x32_bf16 v[120:123], v[166:169], v[180:183], v[120:123]
	v_mfma_f32_16x16x32_bf16 v[116:119], v[144:147], v[188:191], v[116:119]
	v_mfma_f32_16x16x32_bf16 v[112:115], v[166:169], v[188:191], v[112:115]
	v_mfma_f32_16x16x32_bf16 v[108:111], v[144:147], v[208:211], v[108:111]
	v_mfma_f32_16x16x32_bf16 v[104:107], v[166:169], v[208:211], v[104:107]
	v_mfma_f32_16x16x32_bf16 v[100:103], v[144:147], v[222:225], v[100:103]
	v_mfma_f32_16x16x32_bf16 v[96:99], v[166:169], v[222:225], v[96:99]
	v_mfma_f32_16x16x32_bf16 v[124:127], v[148:151], v[184:187], v[124:127]
	v_mfma_f32_16x16x32_bf16 v[120:123], v[176:179], v[184:187], v[120:123]
	v_mfma_f32_16x16x32_bf16 v[116:119], v[148:151], v[204:207], v[116:119]
	v_mfma_f32_16x16x32_bf16 v[112:115], v[176:179], v[204:207], v[112:115]
	v_mfma_f32_16x16x32_bf16 v[108:111], v[148:151], v[218:221], v[108:111]
	v_mfma_f32_16x16x32_bf16 v[104:107], v[176:179], v[218:221], v[104:107]
	v_mfma_f32_16x16x32_bf16 v[100:103], v[148:151], v[226:229], v[100:103]
	v_mfma_f32_16x16x32_bf16 v[96:99], v[176:179], v[226:229], v[96:99]
	s_setprio 0
	s_barrier
; #define PG8_LDA(dst, b, h) do { _Pragma("unroll") for (int m = 0; m < 4; ++m) _Pragma("unroll") for (int k = 0; k < 2; ++k) dst[m][k] = *(const PG8_LAS bf16x8*)(lds + PG8_SA(b, h) + aoff + m * 2048 + k * 1024); } while (0)
; template <class Epi, class Sched, bool ALIGN_EPI = false, bool SP2 = false>
; __device__ __forceinline__ void gemm_phase(PG8_LAS unsigned char* lds, const Gemm g, const Sched& S, const Epi& E) {
;     ...
;             PG8_LDA(At, 1, 1); PG8_STAGE(PG8_SB(1, 0), b3, voffB); PG8_STAGE(PG8_SB(1, 1), b3 + hstepB, voffB); PG8_STAGE(PG8_SA(1, 0), a3, voffA);
;             PG8_WAIT_V(8); PG8_WAIT_L(0); PG8_BAR; PG8_MMA(1, 0, At, B0); PG8_MMA(1, 1, At, B1); PG8_BAR; PG8_SCHED;
;             } else {
;             PG8_LDB(B0, 0, 0); PG8_SCHED; PG8_LDA(At, 0, 0); PG8_STAGE(PG8_SA(1, 1), a1 + hstepA, voffA);
;             PG8_WAIT_L(8); PG8_BAR; PG8_WAIT_L(0); PG8_MMA(0, 0, At, B0); PG8_BAR; PG8_SCHED;
;             PG8_LDB(B1, 0, 1); PG8_STAGE(PG8_SB(0, 0), b2, voffB);
;             PG8_BAR; PG8_WAIT_L(0); PG8_MMA(0, 1, At, B1); PG8_BAR;
;             PG8_LDA(At, 0, 1); PG8_STAGE(PG8_SA(0, 0), a2, voffA);
;             PG8_BAR; PG8_WAIT_L(0); PG8_MMA(1, 0, At, B0); PG8_BAR; PG8_SCHED;
;             PG8_STAGE(PG8_SB(0, 1), b2 + hstepB, voffB);
;             PG8_WAIT_V(6); PG8_BAR; PG8_MMA(1, 1, At, B1); PG8_BAR;
;             PG8_LDB(B0, 1, 0); PG8_SCHED; PG8_LDA(At, 1, 0); PG8_STAGE(PG8_SA(0, 1), a2 + hstepA, voffA);
;             PG8_WAIT_L(8); PG8_BAR; PG8_WAIT_L(0); PG8_MMA(0, 0, At, B0); PG8_BAR; PG8_SCHED;
;             PG8_LDB(B1, 1, 1); PG8_STAGE(PG8_SB(1, 0), b3, voffB);
;             PG8_BAR; PG8_WAIT_L(0); PG8_MMA(0, 1, At, B1); PG8_BAR;
;             PG8_LDA(At, 1, 1); PG8_STAGE(PG8_SA(1, 0), a3, voffA);
;             PG8_BAR; PG8_WAIT_L(0); PG8_MMA(1, 0, At, B0); PG8_BAR; PG8_SCHED;
;             PG8_STAGE(PG8_SB(1, 1), b3 + hstepB, voffB);
;             PG8_WAIT_V(6); PG8_BAR; PG8_MMA(1, 1, At, B1); PG8_BAR;
;             }
;         }
;         if constexpr (ALIGN_EPI) { if (wr == 0) PG8_BAR; }
; __device__ __forceinline__ float row_rstd(const float* ssq, int row, int fq) {
;     const f32x4 v = *(const f32x4*)(ssq + (size_t)row * 16 + fq * 4);
;     float s = (v[0] + v[1]) + (v[2] + v[3]);
;     s += __shfl_xor(s, 16); s += __shfl_xor(s, 32);
;     return __builtin_amdgcn_rsqf(s * (1.f / DM) + EPS);
; }
	s_mov_b32 m0, s84
	v_lshl_add_u64 v[170:171], v[170:171], 0, s[76:77]
	s_add_u32 s14, s14, 0x40080
	ds_read_b128 v[180:183], v175 offset:49152
	ds_read_b128 v[184:187], v175 offset:50176
	ds_read_b128 v[188:191], v175 offset:51200
	ds_read_b128 v[204:207], v175 offset:52224
	ds_read_b128 v[208:211], v175 offset:53248
	ds_read_b128 v[218:221], v175 offset:54272
	ds_read_b128 v[222:225], v175 offset:55296
	ds_read_b128 v[226:229], v175 offset:56320
	global_load_lds_dwordx4 v[170:171], off
	v_lshl_add_u64 v[170:171], v[230:231], 0, s[76:77]
	s_mov_b32 m0, s64
	s_addc_u32 s15, s15, 0
	global_load_lds_dwordx4 v[170:171], off
	v_lshl_add_u64 v[170:171], s[14:15], 0, v[154:155]
	s_mov_b32 m0, s48
	s_nop 0
	global_load_lds_dwordx4 v[170:171], off
	v_lshl_add_u64 v[170:171], s[14:15], 0, v[158:159]
	s_mov_b32 m0, s49
	s_nop 0
	global_load_lds_dwordx4 v[170:171], off
	v_lshl_add_u64 v[170:171], v[232:233], 0, s[76:77]
	s_mov_b32 m0, s65
	s_nop 0
	global_load_lds_dwordx4 v[170:171], off
	v_lshl_add_u64 v[170:171], v[234:235], 0, s[76:77]
	s_mov_b32 m0, s0
	s_nop 0
	global_load_lds_dwordx4 v[170:171], off
	s_waitcnt vmcnt(8)
	s_waitcnt lgkmcnt(0)
	s_barrier
	s_setprio 1
	s_waitcnt lgkmcnt(0)
	v_mfma_f32_16x16x32_bf16 v[28:31], v[128:131], v[180:183], v[28:31]
	v_mfma_f32_16x16x32_bf16 v[24:27], v[136:139], v[180:183], v[24:27]
	v_mfma_f32_16x16x32_bf16 v[20:23], v[128:131], v[188:191], v[20:23]
	v_mfma_f32_16x16x32_bf16 v[16:19], v[136:139], v[188:191], v[16:19]
	v_mfma_f32_16x16x32_bf16 v[12:15], v[128:131], v[208:211], v[12:15]
	v_mfma_f32_16x16x32_bf16 v[8:11], v[136:139], v[208:211], v[8:11]
	v_mfma_f32_16x16x32_bf16 v[4:7], v[128:131], v[222:225], v[4:7]
	v_mfma_f32_16x16x32_bf16 v[0:3], v[136:139], v[222:225], v[0:3]
	v_mfma_f32_16x16x32_bf16 v[28:31], v[132:135], v[184:187], v[28:31]
	v_mfma_f32_16x16x32_bf16 v[24:27], v[140:143], v[184:187], v[24:27]
	v_mfma_f32_16x16x32_bf16 v[20:23], v[132:135], v[204:207], v[20:23]
	v_mfma_f32_16x16x32_bf16 v[16:19], v[140:143], v[204:207], v[16:19]
	v_mfma_f32_16x16x32_bf16 v[12:15], v[132:135], v[218:221], v[12:15]
	v_mfma_f32_16x16x32_bf16 v[8:11], v[140:143], v[218:221], v[8:11]
	v_mfma_f32_16x16x32_bf16 v[4:7], v[132:135], v[226:229], v[4:7]
	v_mfma_f32_16x16x32_bf16 v[0:3], v[140:143], v[226:229], v[0:3]
	s_setprio 0
	s_setprio 1
	v_mfma_f32_16x16x32_bf16 v[92:95], v[144:147], v[180:183], v[92:95]
	v_mfma_f32_16x16x32_bf16 v[88:91], v[166:169], v[180:183], v[88:91]
	v_mfma_f32_16x16x32_bf16 v[84:87], v[144:147], v[188:191], v[84:87]
	v_mfma_f32_16x16x32_bf16 v[80:83], v[166:169], v[188:191], v[80:83]
	v_mfma_f32_16x16x32_bf16 v[76:79], v[144:147], v[208:211], v[76:79]
	v_mfma_f32_16x16x32_bf16 v[72:75], v[166:169], v[208:211], v[72:75]
	v_mfma_f32_16x16x32_bf16 v[68:71], v[144:147], v[222:225], v[68:71]
	v_mfma_f32_16x16x32_bf16 v[64:67], v[166:169], v[222:225], v[64:67]
	v_mfma_f32_16x16x32_bf16 v[92:95], v[148:151], v[184:187], v[92:95]
	v_mfma_f32_16x16x32_bf16 v[88:91], v[176:179], v[184:187], v[88:91]
	v_mfma_f32_16x16x32_bf16 v[84:87], v[148:151], v[204:207], v[84:87]
	v_mfma_f32_16x16x32_bf16 v[80:83], v[176:179], v[204:207], v[80:83]
	v_mfma_f32_16x16x32_bf16 v[76:79], v[148:151], v[218:221], v[76:79]
	v_mfma_f32_16x16x32_bf16 v[72:75], v[176:179], v[218:221], v[72:75]
	v_mfma_f32_16x16x32_bf16 v[68:71], v[148:151], v[226:229], v[68:71]
	v_mfma_f32_16x16x32_bf16 v[64:67], v[176:179], v[226:229], v[64:67]
	s_setprio 0
	s_barrier
	s_add_i32 s22, s22, 2
	s_add_u32 s20, s20, 0x100
	s_addc_u32 s21, s21, 0
	s_add_u32 s12, s12, 0x100
	s_addc_u32 s13, s13, 0
	s_cmp_gt_u32 s22, 13
	s_cbranch_scc0 .LBB0_380
	s_cmp_eq_u32 s10, 14
	s_cbranch_scc1 .Lewh_skip
	v_lshl_add_u32 v214, s8, 8, v172
	v_mov_b32_e32 v128, v214
	v_ashrrev_i32_e32 v129, 31, v128
	v_lshlrev_b64 v[128:129], 6, v[128:129]
	v_lshl_add_u64 v[128:129], v[160:161], 0, v[128:129]
	global_load_dwordx4 v[128:131], v[128:129], off
	v_add_u32_e32 v132, 16, v214
	v_ashrrev_i32_e32 v133, 31, v132
	v_lshlrev_b64 v[132:133], 6, v[132:133]
	v_lshl_add_u64 v[132:133], v[160:161], 0, v[132:133]
	global_load_dwordx4 v[132:135], v[132:133], off
	v_add_u32_e32 v136, 32, v214
	v_ashrrev_i32_e32 v137, 31, v136
	v_lshlrev_b64 v[136:137], 6, v[136:137]
	v_lshl_add_u64 v[136:137], v[160:161], 0, v[136:137]
	global_load_dwordx4 v[136:139], v[136:137], off
	v_add_u32_e32 v140, 48, v214
	v_ashrrev_i32_e32 v141, 31, v140
	v_lshlrev_b64 v[140:141], 6, v[140:141]
	v_lshl_add_u64 v[140:141], v[160:161], 0, v[140:141]
	global_load_dwordx4 v[140:143], v[140:141], off
	v_add_u32_e32 v144, 0x80, v214
	v_ashrrev_i32_e32 v145, 31, v144
	v_lshlrev_b64 v[144:145], 6, v[144:145]
	v_lshl_add_u64 v[144:145], v[160:161], 0, v[144:145]
	global_load_dwordx4 v[144:147], v[144:145], off
	v_add_u32_e32 v148, 0x90, v214
	v_ashrrev_i32_e32 v149, 31, v148
	v_lshlrev_b64 v[148:149], 6, v[148:149]
	v_lshl_add_u64 v[148:149], v[160:161], 0, v[148:149]
	global_load_dwordx4 v[148:151], v[148:149], off
	v_add_u32_e32 v236, 0xa0, v214
	v_ashrrev_i32_e32 v237, 31, v236
	v_lshlrev_b64 v[236:237], 6, v[236:237]
	v_lshl_add_u64 v[236:237], v[160:161], 0, v[236:237]
	global_load_dwordx4 v[236:239], v[236:237], off
	v_add_u32_e32 v246, 0xb0, v214
	v_ashrrev_i32_e32 v247, 31, v246
	v_lshlrev_b64 v[246:247], 6, v[246:247]
	v_lshl_add_u64 v[246:247], v[160:161], 0, v[246:247]
	global_load_dwordx4 v[246:249], v[246:247], off
.Lewh_skip:
	s_and_b64 vcc, exec, s[36:37]
	s_cbranch_vccz .LBB0_383
	s_barrier

; __device__ __forceinline__ float silu_f(float x) { return x * __builtin_amdgcn_rcpf(1.f + __expf(-x)); }
; __device__ __forceinline__ v4u pack8(const f32x4 a, const f32x4 b) { v4u w; w.x = cvt_pk_bf16(a[0], a[1]); w.y = cvt_pk_bf16(a[2], a[3]); w.z = cvt_pk_bf16(b[0], b[1]); w.w = cvt_pk_bf16(b[2], b[3]); return w; }
; __device__ __forceinline__ float row_rstd(const float* ssq, int row, int fq) {
;     const f32x4 v = *(const f32x4*)(ssq + (size_t)row * 16 + fq * 4);
;     float s = (v[0] + v[1]) + (v[2] + v[3]);
;     s += __shfl_xor(s, 16); s += __shfl_xor(s, 32);
;     return __builtin_amdgcn_rsqf(s * (1.f / DM) + EPS);
; }
;     __device__ __forceinline__ void operator()(const f32x4 (&acc)[2][2][4][2], const pg8::Unit& u, int wr, int wc, int fr, int fq) const {
;     ...
;         const int grp = pn >> 1, cb = (pn & 1) * 256 + cw;
;     ...
;         if (grp == 0) { WIN_LOOP( _Pragma("unroll") for (int i = 0; i < 4; ++i) { a[i] = silu_f(a[i]); b[i] = silu_f(b[i]); } *(v4u*)(QO + (size_t)row * DM + c) = pack8(a, b); ) }
;         else if (grp == 3) { WIN_LOOP( _Pragma("unroll") for (int i = 0; i < 4; ++i) { a[i] = silu_f(a[i]); b[i] = silu_f(b[i]); } *(v4u*)(GH + (size_t)row * 512 + c) = pack8(a, b); ) }
;         else if (grp == 1) {
;             f32x4 l0[2], l1[2];
; #pragma unroll
;             for (int bj = 0; bj < 2; ++bj) { l0[bj] = *(const f32x4*)(lb + cb + bj * 128); l1[bj] = *(const f32x4*)(lb + cb + bj * 128 + 4); }
;             WIN_LOOP( _Pragma("unroll") for (int i = 0; i < 4; ++i) { const float s0 = fminf(a[i], 0.f) - __logf(1.f + __expf(-fabsf(a[i]))), s1 = fminf(b[i], 0.f) - __logf(1.f + __expf(-fabsf(b[i]))); const float la = l0[bj][i], lbv = l1[bj][i];
;                     a[i] = la > 0.f ? __logf(la + (1.f - la) * __expf(s0)) : s0; b[i] = lbv > 0.f ? __logf(lbv + (1.f - lbv) * __expf(s1)) : s1; }
;                 *(f32x4*)(LF + (size_t)row * 512 + c) = a; *(f32x4*)(LF + (size_t)row * 512 + c + 4) = b; __builtin_amdgcn_sched_barrier(0); ) }
;         else if (grp == 2) { WIN_LOOP( *(v4u*)(VH + (size_t)row * 512 + c) = pack8(a, b); ) }
;         else if (grp == 4) { WIN_LOOP( *(v4u*)(QO + (size_t)row * DM + 512 + c) = pack8(a * C2Q, b * C2Q); ) }
;         else if (grp == 5) { WIN_LOOP( *(v4u*)(FK + (size_t)row * 512 + c) = pack8(a, b); ) }
.LBB0_394:
	s_waitcnt vmcnt(0)
	v_add_f32_e32 v128, v128, v129
	v_add_f32_e32 v130, v130, v131
	v_add_f32_e32 v132, v132, v133
	v_add_f32_e32 v134, v134, v135
	v_add_f32_e32 v136, v136, v137
	v_add_f32_e32 v138, v138, v139
	v_add_f32_e32 v140, v140, v141
	v_add_f32_e32 v142, v142, v143
	v_add_f32_e32 v144, v144, v145
	v_add_f32_e32 v146, v146, v147
	v_add_f32_e32 v148, v148, v149
	v_add_f32_e32 v150, v150, v151
	v_add_f32_e32 v236, v236, v237
	v_add_f32_e32 v238, v238, v239
	v_add_f32_e32 v246, v246, v247
	v_add_f32_e32 v248, v248, v249
	v_add_f32_e32 v128, v128, v130
	v_add_f32_e32 v132, v132, v134
	v_add_f32_e32 v136, v136, v138
	v_add_f32_e32 v140, v140, v142
	v_add_f32_e32 v144, v144, v146
	v_add_f32_e32 v148, v148, v150
	v_add_f32_e32 v236, v236, v238
	v_add_f32_e32 v246, v246, v248
	v_xor_b32_e32 v130, 16, v215
	v_xor_b32_e32 v131, 32, v215
	v_lshlrev_b32_e32 v130, 2, v130
	v_lshlrev_b32_e32 v131, 2, v131
	ds_bpermute_b32 v129, v130, v128
	ds_bpermute_b32 v133, v130, v132
	ds_bpermute_b32 v137, v130, v136
	ds_bpermute_b32 v141, v130, v140
	ds_bpermute_b32 v145, v130, v144
	ds_bpermute_b32 v149, v130, v148
	ds_bpermute_b32 v237, v130, v236
	ds_bpermute_b32 v247, v130, v246
	s_waitcnt lgkmcnt(0)
	v_add_f32_e32 v128, v128, v129
	v_add_f32_e32 v132, v132, v133
	v_add_f32_e32 v136, v136, v137
	v_add_f32_e32 v140, v140, v141
	v_add_f32_e32 v144, v144, v145
	v_add_f32_e32 v148, v148, v149
	v_add_f32_e32 v236, v236, v237
	v_add_f32_e32 v246, v246, v247
	ds_bpermute_b32 v129, v131, v128
	ds_bpermute_b32 v133, v131, v132
	ds_bpermute_b32 v137, v131, v136
	ds_bpermute_b32 v141, v131, v140
	ds_bpermute_b32 v145, v131, v144
	ds_bpermute_b32 v149, v131, v148
	ds_bpermute_b32 v237, v131, v236
	ds_bpermute_b32 v247, v131, v246
	s_waitcnt lgkmcnt(0)
	v_add_f32_e32 v128, v128, v129
	v_add_f32_e32 v132, v132, v133
	v_add_f32_e32 v136, v136, v137
	v_add_f32_e32 v140, v140, v141
	v_add_f32_e32 v144, v144, v145
	v_add_f32_e32 v148, v148, v149
	v_add_f32_e32 v236, v236, v237
	v_add_f32_e32 v246, v246, v247
	v_fmamk_f32 v128, v128, 0x3a800000, v212
	v_fmamk_f32 v132, v132, 0x3a800000, v212
	v_fmamk_f32 v136, v136, 0x3a800000, v212
	v_fmamk_f32 v140, v140, 0x3a800000, v212
	v_fmamk_f32 v144, v144, 0x3a800000, v212
	v_fmamk_f32 v148, v148, 0x3a800000, v212
	v_fmamk_f32 v236, v236, 0x3a800000, v212
	v_fmamk_f32 v246, v246, 0x3a800000, v212
	v_rsq_f32_e32 v250, v128
	v_rsq_f32_e32 v251, v132
	v_rsq_f32_e32 v252, v136
	v_rsq_f32_e32 v253, v140
	v_rsq_f32_e32 v254, v144
	v_rsq_f32_e32 v240, v148
	v_rsq_f32_e32 v241, v236
	v_rsq_f32_e32 v245, v246
	s_nop 0
	s_lshl_b32 s8, s2, 8
	s_and_b32 s8, s8, 0x100
	v_or_b32_e32 v176, s8, v174
	s_cmp_gt_u32 s2, 1
	s_mov_b64 s[8:9], -1
	s_cbranch_scc0 .LBB0_417
	s_ashr_i32 s14, s2, 1
	s_mov_b64 s[12:13], -1
	s_mov_b64 s[8:9], 0
	s_cmp_lt_i32 s14, 3
	s_mov_b64 s[10:11], 0
	s_cbranch_scc1 .LBB0_407
	s_cmp_gt_i32 s14, 3
	s_cbranch_scc0 .LBB0_404
	s_cmp_gt_i32 s14, 4
	s_cbranch_scc0 .LBB0_401
	s_cmp_eq_u32 s14, 5
	s_mov_b64 s[10:11], -1
	s_cbranch_scc0 .LBB0_400
	v_and_b32_e32 v129, 64, v215
	v_xor_b32_e32 v128, 16, v215
	v_add_u32_e32 v129, 64, v129
	v_cmp_lt_i32_e32 vcc, v128, v129
	v_ashrrev_i32_e32 v167, 31, v166
	v_readlane_b32 s10, v255, 41
	v_cndmask_b32_e32 v128, v215, v128, vcc
	v_lshlrev_b32_e32 v130, 2, v128
	v_xor_b32_e32 v128, 32, v215
	v_cmp_lt_i32_e32 vcc, v128, v129
	v_readlane_b32 s11, v255, 42
	v_lshlrev_b32_e32 v192, 1, v176
	v_cndmask_b32_e32 v128, v215, v128, vcc
	v_lshlrev_b32_e32 v131, 2, v128
	v_lshlrev_b64 v[128:129], 6, v[166:167]
	v_lshl_add_u64 v[128:129], v[160:161], 0, v[128:129]
	s_nop 0
	s_waitcnt lgkmcnt(0)
	s_nop 3
	v_lshlrev_b64 v[132:133], 10, v[166:167]
	s_nop 1
	v_lshl_add_u64 v[136:137], s[10:11], 0, v[132:133]
	v_lshl_add_u64 v[136:137], v[136:137], 0, v[192:193]
	s_waitcnt lgkmcnt(0)
	s_nop 1
	s_waitcnt lgkmcnt(0)
	s_nop 1
	v_mov_b32_e32 v128, v250
	s_nop 0
	v_pk_mul_f32 v[134:135], v[62:63], v[128:129] op_sel_hi:[1,0]
	v_pk_mul_f32 v[132:133], v[60:61], v[128:129] op_sel_hi:[1,0]
	v_pk_mul_f32 v[138:139], v[58:59], v[128:129] op_sel_hi:[1,0]
	v_pk_mul_f32 v[140:141], v[56:57], v[128:129] op_sel_hi:[1,0]
	v_cvt_pk_bf16_f32 v132, v132, v133
	v_cvt_pk_bf16_f32 v133, v134, v135
	v_cvt_pk_bf16_f32 v134, v140, v141
	v_cvt_pk_bf16_f32 v135, v138, v139
	global_store_dwordx4 v[136:137], v[132:135], off
	v_pk_mul_f32 v[138:139], v[122:123], v[128:129] op_sel_hi:[1,0]
	s_nop 0
	v_pk_mul_f32 v[134:135], v[126:127], v[128:129] op_sel_hi:[1,0]
	v_pk_mul_f32 v[132:133], v[124:125], v[128:129] op_sel_hi:[1,0]
	v_pk_mul_f32 v[128:129], v[120:121], v[128:129] op_sel_hi:[1,0]
	v_cvt_pk_bf16_f32 v132, v132, v133
	v_cvt_pk_bf16_f32 v133, v134, v135
	v_cvt_pk_bf16_f32 v134, v128, v129
	v_or_b32_e32 v128, 16, v166
	v_cvt_pk_bf16_f32 v135, v138, v139
	v_ashrrev_i32_e32 v129, 31, v128
	global_store_dwordx4 v[136:137], v[132:135], off offset:256
	s_nop 1
	v_lshlrev_b64 v[132:133], 6, v[128:129]
	v_lshl_add_u64 v[132:133], v[160:161], 0, v[132:133]
	s_nop 0
	v_lshlrev_b64 v[128:129], 10, v[128:129]
	v_lshl_add_u64 v[128:129], s[10:11], 0, v[128:129]
	v_lshl_add_u64 v[128:129], v[128:129], 0, v[192:193]
	s_waitcnt lgkmcnt(0)
	s_nop 3
	s_nop 0
	s_nop 1
	s_waitcnt lgkmcnt(0)
	s_nop 1
	s_waitcnt lgkmcnt(0)
; __device__ __forceinline__ float silu_f(float x) { return x * __builtin_amdgcn_rcpf(1.f + __expf(-x)); }
; __device__ __forceinline__ v4u pack8(const f32x4 a, const f32x4 b) { v4u w; w.x = cvt_pk_bf16(a[0], a[1]); w.y = cvt_pk_bf16(a[2], a[3]); w.z = cvt_pk_bf16(b[0], b[1]); w.w = cvt_pk_bf16(b[2], b[3]); return w; }
;     __device__ __forceinline__ void operator()(const f32x4 (&acc)[2][2][4][2], const pg8::Unit& u, int wr, int wc, int fr, int fq) const {
;     ...
;         if (grp == 0) { WIN_LOOP( _Pragma("unroll") for (int i = 0; i < 4; ++i) { a[i] = silu_f(a[i]); b[i] = silu_f(b[i]); } *(v4u*)(QO + (size_t)row * DM + c) = pack8(a, b); ) }
;         else if (grp == 3) { WIN_LOOP( _Pragma("unroll") for (int i = 0; i < 4; ++i) { a[i] = silu_f(a[i]); b[i] = silu_f(b[i]); } *(v4u*)(GH + (size_t)row * 512 + c) = pack8(a, b); ) }
;         else if (grp == 1) {
;             f32x4 l0[2], l1[2];
; #pragma unroll
;             for (int bj = 0; bj < 2; ++bj) { l0[bj] = *(const f32x4*)(lb + cb + bj * 128); l1[bj] = *(const f32x4*)(lb + cb + bj * 128 + 4); }
;             WIN_LOOP( _Pragma("unroll") for (int i = 0; i < 4; ++i) { const float s0 = fminf(a[i], 0.f) - __logf(1.f + __expf(-fabsf(a[i]))), s1 = fminf(b[i], 0.f) - __logf(1.f + __expf(-fabsf(b[i]))); const float la = l0[bj][i], lbv = l1[bj][i];
;                     a[i] = la > 0.f ? __logf(la + (1.f - la) * __expf(s0)) : s0; b[i] = lbv > 0.f ? __logf(lbv + (1.f - lbv) * __expf(s1)) : s1; }
;                 *(f32x4*)(LF + (size_t)row * 512 + c) = a; *(f32x4*)(LF + (size_t)row * 512 + c + 4) = b; __builtin_amdgcn_sched_barrier(0); ) }
;         else if (grp == 2) { WIN_LOOP( *(v4u*)(VH + (size_t)row * 512 + c) = pack8(a, b); ) }
;         else if (grp == 4) { WIN_LOOP( *(v4u*)(QO + (size_t)row * DM + 512 + c) = pack8(a * C2Q, b * C2Q); ) }
;         else if (grp == 5) { WIN_LOOP( *(v4u*)(FK + (size_t)row * 512 + c) = pack8(a, b); ) }
	s_nop 1
	v_mov_b32_e32 v136, v251
	s_nop 0
	v_pk_mul_f32 v[134:135], v[54:55], v[136:137] op_sel_hi:[1,0]
	v_pk_mul_f32 v[132:133], v[52:53], v[136:137] op_sel_hi:[1,0]
	v_pk_mul_f32 v[138:139], v[50:51], v[136:137] op_sel_hi:[1,0]
	v_pk_mul_f32 v[140:141], v[48:49], v[136:137] op_sel_hi:[1,0]
	v_cvt_pk_bf16_f32 v132, v132, v133
	v_cvt_pk_bf16_f32 v133, v134, v135
	v_cvt_pk_bf16_f32 v134, v140, v141
	v_cvt_pk_bf16_f32 v135, v138, v139
	global_store_dwordx4 v[128:129], v[132:135], off
	v_pk_mul_f32 v[138:139], v[114:115], v[136:137] op_sel_hi:[1,0]
	s_nop 0
	v_pk_mul_f32 v[134:135], v[118:119], v[136:137] op_sel_hi:[1,0]
	v_pk_mul_f32 v[132:133], v[116:117], v[136:137] op_sel_hi:[1,0]
	v_pk_mul_f32 v[136:137], v[112:113], v[136:137] op_sel_hi:[1,0]
	v_cvt_pk_bf16_f32 v132, v132, v133
	v_cvt_pk_bf16_f32 v133, v134, v135
	v_cvt_pk_bf16_f32 v134, v136, v137
	v_cvt_pk_bf16_f32 v135, v138, v139
	global_store_dwordx4 v[128:129], v[132:135], off offset:256
	v_or_b32_e32 v128, 32, v166
	v_ashrrev_i32_e32 v129, 31, v128
	v_lshlrev_b64 v[132:133], 6, v[128:129]
	v_lshl_add_u64 v[132:133], v[160:161], 0, v[132:133]
	s_nop 0
	v_lshlrev_b64 v[128:129], 10, v[128:129]
	v_lshl_add_u64 v[128:129], s[10:11], 0, v[128:129]
	v_lshl_add_u64 v[128:129], v[128:129], 0, v[192:193]
	s_waitcnt lgkmcnt(0)
	s_nop 3
	s_nop 0
	s_nop 1
	s_waitcnt lgkmcnt(0)
	s_nop 1
	s_waitcnt lgkmcnt(0)
	s_nop 1
	v_mov_b32_e32 v136, v252
	s_nop 0
	v_pk_mul_f32 v[134:135], v[46:47], v[136:137] op_sel_hi:[1,0]
	v_pk_mul_f32 v[132:133], v[44:45], v[136:137] op_sel_hi:[1,0]
	v_pk_mul_f32 v[138:139], v[42:43], v[136:137] op_sel_hi:[1,0]
	v_pk_mul_f32 v[140:141], v[40:41], v[136:137] op_sel_hi:[1,0]
	v_cvt_pk_bf16_f32 v132, v132, v133
	v_cvt_pk_bf16_f32 v133, v134, v135
	v_cvt_pk_bf16_f32 v134, v140, v141
	v_cvt_pk_bf16_f32 v135, v138, v139
	global_store_dwordx4 v[128:129], v[132:135], off
	v_pk_mul_f32 v[138:139], v[106:107], v[136:137] op_sel_hi:[1,0]
	s_nop 0
	v_pk_mul_f32 v[134:135], v[110:111], v[136:137] op_sel_hi:[1,0]
	v_pk_mul_f32 v[132:133], v[108:109], v[136:137] op_sel_hi:[1,0]
	v_pk_mul_f32 v[136:137], v[104:105], v[136:137] op_sel_hi:[1,0]
	v_cvt_pk_bf16_f32 v132, v132, v133
	v_cvt_pk_bf16_f32 v133, v134, v135
	v_cvt_pk_bf16_f32 v134, v136, v137
	v_cvt_pk_bf16_f32 v135, v138, v139
	global_store_dwordx4 v[128:129], v[132:135], off offset:256
	v_or_b32_e32 v128, 48, v166
	v_ashrrev_i32_e32 v129, 31, v128
	v_lshlrev_b64 v[132:133], 6, v[128:129]
	v_lshl_add_u64 v[132:133], v[160:161], 0, v[132:133]
	s_nop 0
	v_lshlrev_b64 v[128:129], 10, v[128:129]
	v_lshl_add_u64 v[128:129], s[10:11], 0, v[128:129]
	v_lshl_add_u64 v[128:129], v[128:129], 0, v[192:193]
	s_waitcnt lgkmcnt(0)
	s_nop 3
	s_nop 0
	s_nop 1
	s_waitcnt lgkmcnt(0)
	s_nop 1
	s_waitcnt lgkmcnt(0)
	s_nop 1
	v_mov_b32_e32 v136, v253
	s_nop 0
	v_pk_mul_f32 v[134:135], v[38:39], v[136:137] op_sel_hi:[1,0]
	v_pk_mul_f32 v[132:133], v[36:37], v[136:137] op_sel_hi:[1,0]
	v_pk_mul_f32 v[138:139], v[34:35], v[136:137] op_sel_hi:[1,0]
	v_pk_mul_f32 v[140:141], v[32:33], v[136:137] op_sel_hi:[1,0]
	v_cvt_pk_bf16_f32 v132, v132, v133
	v_cvt_pk_bf16_f32 v133, v134, v135
	v_cvt_pk_bf16_f32 v134, v140, v141
	v_cvt_pk_bf16_f32 v135, v138, v139
	global_store_dwordx4 v[128:129], v[132:135], off
	v_pk_mul_f32 v[138:139], v[98:99], v[136:137] op_sel_hi:[1,0]
	s_nop 0
	v_pk_mul_f32 v[134:135], v[102:103], v[136:137] op_sel_hi:[1,0]
	v_pk_mul_f32 v[132:133], v[100:101], v[136:137] op_sel_hi:[1,0]
	v_pk_mul_f32 v[136:137], v[96:97], v[136:137] op_sel_hi:[1,0]
	v_cvt_pk_bf16_f32 v132, v132, v133
	v_cvt_pk_bf16_f32 v133, v134, v135
	v_cvt_pk_bf16_f32 v134, v136, v137
	v_cvt_pk_bf16_f32 v135, v138, v139
	global_store_dwordx4 v[128:129], v[132:135], off offset:256
	v_add_u32_e32 v128, 0x80, v166
	v_ashrrev_i32_e32 v129, 31, v128
	v_lshlrev_b64 v[132:133], 6, v[128:129]
	v_lshl_add_u64 v[132:133], v[160:161], 0, v[132:133]
	s_nop 0
	v_lshlrev_b64 v[128:129], 10, v[128:129]
	v_lshl_add_u64 v[128:129], s[10:11], 0, v[128:129]
	v_lshl_add_u64 v[128:129], v[128:129], 0, v[192:193]
	s_waitcnt lgkmcnt(0)
	s_nop 3
	s_nop 0
	s_nop 1
	s_waitcnt lgkmcnt(0)
	s_nop 1
	s_waitcnt lgkmcnt(0)
; __device__ __forceinline__ float silu_f(float x) { return x * __builtin_amdgcn_rcpf(1.f + __expf(-x)); }
; __device__ __forceinline__ v4u pack8(const f32x4 a, const f32x4 b) { v4u w; w.x = cvt_pk_bf16(a[0], a[1]); w.y = cvt_pk_bf16(a[2], a[3]); w.z = cvt_pk_bf16(b[0], b[1]); w.w = cvt_pk_bf16(b[2], b[3]); return w; }
;     __device__ __forceinline__ void operator()(const f32x4 (&acc)[2][2][4][2], const pg8::Unit& u, int wr, int wc, int fr, int fq) const {
;     ...
;         if (grp == 0) { WIN_LOOP( _Pragma("unroll") for (int i = 0; i < 4; ++i) { a[i] = silu_f(a[i]); b[i] = silu_f(b[i]); } *(v4u*)(QO + (size_t)row * DM + c) = pack8(a, b); ) }
;         else if (grp == 3) { WIN_LOOP( _Pragma("unroll") for (int i = 0; i < 4; ++i) { a[i] = silu_f(a[i]); b[i] = silu_f(b[i]); } *(v4u*)(GH + (size_t)row * 512 + c) = pack8(a, b); ) }
;         else if (grp == 1) {
;             f32x4 l0[2], l1[2];
; #pragma unroll
;             for (int bj = 0; bj < 2; ++bj) { l0[bj] = *(const f32x4*)(lb + cb + bj * 128); l1[bj] = *(const f32x4*)(lb + cb + bj * 128 + 4); }
;             WIN_LOOP( _Pragma("unroll") for (int i = 0; i < 4; ++i) { const float s0 = fminf(a[i], 0.f) - __logf(1.f + __expf(-fabsf(a[i]))), s1 = fminf(b[i], 0.f) - __logf(1.f + __expf(-fabsf(b[i]))); const float la = l0[bj][i], lbv = l1[bj][i];
;                     a[i] = la > 0.f ? __logf(la + (1.f - la) * __expf(s0)) : s0; b[i] = lbv > 0.f ? __logf(lbv + (1.f - lbv) * __expf(s1)) : s1; }
;                 *(f32x4*)(LF + (size_t)row * 512 + c) = a; *(f32x4*)(LF + (size_t)row * 512 + c + 4) = b; __builtin_amdgcn_sched_barrier(0); ) }
;         else if (grp == 2) { WIN_LOOP( *(v4u*)(VH + (size_t)row * 512 + c) = pack8(a, b); ) }
;         else if (grp == 4) { WIN_LOOP( *(v4u*)(QO + (size_t)row * DM + 512 + c) = pack8(a * C2Q, b * C2Q); ) }
;         else if (grp == 5) { WIN_LOOP( *(v4u*)(FK + (size_t)row * 512 + c) = pack8(a, b); ) }
	s_nop 1
	v_mov_b32_e32 v136, v254
	s_nop 0
	v_pk_mul_f32 v[134:135], v[30:31], v[136:137] op_sel_hi:[1,0]
	v_pk_mul_f32 v[132:133], v[28:29], v[136:137] op_sel_hi:[1,0]
	v_pk_mul_f32 v[138:139], v[26:27], v[136:137] op_sel_hi:[1,0]
	v_pk_mul_f32 v[140:141], v[24:25], v[136:137] op_sel_hi:[1,0]
	v_cvt_pk_bf16_f32 v132, v132, v133
	v_cvt_pk_bf16_f32 v133, v134, v135
	v_cvt_pk_bf16_f32 v134, v140, v141
	v_cvt_pk_bf16_f32 v135, v138, v139
	global_store_dwordx4 v[128:129], v[132:135], off
	v_pk_mul_f32 v[138:139], v[90:91], v[136:137] op_sel_hi:[1,0]
	s_nop 0
	v_pk_mul_f32 v[134:135], v[94:95], v[136:137] op_sel_hi:[1,0]
	v_pk_mul_f32 v[132:133], v[92:93], v[136:137] op_sel_hi:[1,0]
	v_pk_mul_f32 v[136:137], v[88:89], v[136:137] op_sel_hi:[1,0]
	v_cvt_pk_bf16_f32 v132, v132, v133
	v_cvt_pk_bf16_f32 v133, v134, v135
	v_cvt_pk_bf16_f32 v134, v136, v137
	v_cvt_pk_bf16_f32 v135, v138, v139
	global_store_dwordx4 v[128:129], v[132:135], off offset:256
	v_add_u32_e32 v128, 0x90, v166
	v_ashrrev_i32_e32 v129, 31, v128
	v_lshlrev_b64 v[132:133], 6, v[128:129]
	v_lshl_add_u64 v[132:133], v[160:161], 0, v[132:133]
	s_nop 0
	v_lshlrev_b64 v[128:129], 10, v[128:129]
	v_lshl_add_u64 v[128:129], s[10:11], 0, v[128:129]
	v_lshl_add_u64 v[128:129], v[128:129], 0, v[192:193]
	s_waitcnt lgkmcnt(0)
	s_nop 3
	s_nop 0
	s_nop 1
	s_waitcnt lgkmcnt(0)
	s_nop 1
	s_waitcnt lgkmcnt(0)
	s_nop 1
	v_mov_b32_e32 v136, v240
	s_nop 0
	v_pk_mul_f32 v[134:135], v[22:23], v[136:137] op_sel_hi:[1,0]
	v_pk_mul_f32 v[132:133], v[20:21], v[136:137] op_sel_hi:[1,0]
	v_pk_mul_f32 v[138:139], v[18:19], v[136:137] op_sel_hi:[1,0]
	v_pk_mul_f32 v[140:141], v[16:17], v[136:137] op_sel_hi:[1,0]
	v_cvt_pk_bf16_f32 v132, v132, v133
	v_cvt_pk_bf16_f32 v133, v134, v135
	v_cvt_pk_bf16_f32 v134, v140, v141
	v_cvt_pk_bf16_f32 v135, v138, v139
	global_store_dwordx4 v[128:129], v[132:135], off
	v_pk_mul_f32 v[138:139], v[82:83], v[136:137] op_sel_hi:[1,0]
	s_nop 0
	v_pk_mul_f32 v[134:135], v[86:87], v[136:137] op_sel_hi:[1,0]
	v_pk_mul_f32 v[132:133], v[84:85], v[136:137] op_sel_hi:[1,0]
	v_pk_mul_f32 v[136:137], v[80:81], v[136:137] op_sel_hi:[1,0]
	v_cvt_pk_bf16_f32 v132, v132, v133
	v_cvt_pk_bf16_f32 v133, v134, v135
	v_cvt_pk_bf16_f32 v134, v136, v137
	v_cvt_pk_bf16_f32 v135, v138, v139
	global_store_dwordx4 v[128:129], v[132:135], off offset:256
	v_add_u32_e32 v128, 0xa0, v166
	v_ashrrev_i32_e32 v129, 31, v128
	v_lshlrev_b64 v[132:133], 6, v[128:129]
	v_lshl_add_u64 v[132:133], v[160:161], 0, v[132:133]
	s_nop 0
	v_lshlrev_b64 v[128:129], 10, v[128:129]
	v_lshl_add_u64 v[128:129], s[10:11], 0, v[128:129]
	v_lshl_add_u64 v[128:129], v[128:129], 0, v[192:193]
	s_waitcnt lgkmcnt(0)
	s_nop 3
	s_nop 0
	s_nop 1
	s_waitcnt lgkmcnt(0)
	s_nop 1
	s_waitcnt lgkmcnt(0)
	s_nop 1
	v_mov_b32_e32 v136, v241
	s_nop 0
	v_pk_mul_f32 v[134:135], v[14:15], v[136:137] op_sel_hi:[1,0]
	v_pk_mul_f32 v[132:133], v[12:13], v[136:137] op_sel_hi:[1,0]
	v_pk_mul_f32 v[138:139], v[10:11], v[136:137] op_sel_hi:[1,0]
	v_pk_mul_f32 v[140:141], v[8:9], v[136:137] op_sel_hi:[1,0]
	v_cvt_pk_bf16_f32 v132, v132, v133
	v_cvt_pk_bf16_f32 v133, v134, v135
	v_cvt_pk_bf16_f32 v134, v140, v141
	v_cvt_pk_bf16_f32 v135, v138, v139
	global_store_dwordx4 v[128:129], v[132:135], off
	v_pk_mul_f32 v[138:139], v[74:75], v[136:137] op_sel_hi:[1,0]
	s_nop 0
	v_pk_mul_f32 v[134:135], v[78:79], v[136:137] op_sel_hi:[1,0]
	v_pk_mul_f32 v[132:133], v[76:77], v[136:137] op_sel_hi:[1,0]
	v_pk_mul_f32 v[136:137], v[72:73], v[136:137] op_sel_hi:[1,0]
	v_cvt_pk_bf16_f32 v132, v132, v133
	v_cvt_pk_bf16_f32 v133, v134, v135
	v_cvt_pk_bf16_f32 v134, v136, v137
	v_cvt_pk_bf16_f32 v135, v138, v139
	global_store_dwordx4 v[128:129], v[132:135], off offset:256
	v_add_u32_e32 v128, 0xb0, v166
	v_ashrrev_i32_e32 v129, 31, v128
	v_lshlrev_b64 v[132:133], 6, v[128:129]
	v_lshl_add_u64 v[132:133], v[160:161], 0, v[132:133]
	s_nop 0
	v_lshlrev_b64 v[128:129], 10, v[128:129]
	s_waitcnt lgkmcnt(0)
	s_nop 3
	v_lshl_add_u64 v[134:135], s[10:11], 0, v[128:129]
	s_nop 1
	v_lshl_add_u64 v[134:135], v[134:135], 0, v[192:193]
	s_mov_b64 s[10:11], 0
	s_waitcnt lgkmcnt(0)
	s_nop 1
	s_waitcnt lgkmcnt(0)
	s_nop 1
	v_mov_b32_e32 v132, v245
	s_nop 0
	v_pk_mul_f32 v[130:131], v[6:7], v[132:133] op_sel_hi:[1,0]
	v_pk_mul_f32 v[128:129], v[4:5], v[132:133] op_sel_hi:[1,0]
	v_pk_mul_f32 v[136:137], v[2:3], v[132:133] op_sel_hi:[1,0]
	v_pk_mul_f32 v[138:139], v[0:1], v[132:133] op_sel_hi:[1,0]
	v_cvt_pk_bf16_f32 v128, v128, v129
	v_cvt_pk_bf16_f32 v129, v130, v131
	v_cvt_pk_bf16_f32 v130, v138, v139
	v_cvt_pk_bf16_f32 v131, v136, v137
	global_store_dwordx4 v[134:135], v[128:131], off
	v_pk_mul_f32 v[136:137], v[66:67], v[132:133] op_sel_hi:[1,0]
	s_nop 0
	v_pk_mul_f32 v[130:131], v[70:71], v[132:133] op_sel_hi:[1,0]
	v_pk_mul_f32 v[128:129], v[68:69], v[132:133] op_sel_hi:[1,0]
	v_pk_mul_f32 v[132:133], v[64:65], v[132:133] op_sel_hi:[1,0]
	v_cvt_pk_bf16_f32 v128, v128, v129
	v_cvt_pk_bf16_f32 v129, v130, v131
	v_cvt_pk_bf16_f32 v130, v132, v133
	v_cvt_pk_bf16_f32 v131, v136, v137
	global_store_dwordx4 v[134:135], v[128:131], off offset:256

; #define PG8_STAGE(bufoff, gbase, voff) do { _Pragma("unroll") for (int _i = 0; _i < 2; ++_i) \
;         __builtin_amdgcn_global_load_lds((const unsigned*)((const char*)(gbase) + (voff)[_i]), (PG8_LAS unsigned*)(lds + (bufoff) + ldsw + _i * 8192), 16, 0, 0); } while (0)
; #define PG8_LDA(dst, b, h) do { _Pragma("unroll") for (int m = 0; m < 4; ++m) _Pragma("unroll") for (int k = 0; k < 2; ++k) dst[m][k] = *(const PG8_LAS bf16x8*)(lds + PG8_SA(b, h) + aoff + m * 2048 + k * 1024); } while (0)
; #define PG8_LDB(dst, b, h) do { _Pragma("unroll") for (int n = 0; n < 2; ++n) _Pragma("unroll") for (int k = 0; k < 2; ++k) dst[n][k] = *(const PG8_LAS bf16x8*)(lds + PG8_SB(b, h) + boff + n * 2048 + k * 1024); } while (0)
; #define PG8_MMA(ai, bj, At, Bt) do { __builtin_amdgcn_s_setprio(1); _Pragma("unroll") for (int m = 0; m < 4; ++m) _Pragma("unroll") for (int n = 0; n < 2; ++n) _Pragma("unroll") for (int k = 0; k < 2; ++k) \
;         acc[ai][bj][m][n] = __builtin_amdgcn_mfma_f32_16x16x32_bf16(Bt[n][k], At[m][k], acc[ai][bj][m][n], 0, 0, 0); __builtin_amdgcn_s_setprio(0); } while (0)
; #define PG8_WAIT_V(n) asm volatile("s_waitcnt vmcnt(" #n ")" ::: "memory")
; #define PG8_WAIT_L(n) asm volatile("s_waitcnt lgkmcnt(" #n ")" ::: "memory")
; #define PG8_BAR __builtin_amdgcn_s_barrier()
; #define PG8_SCHED __builtin_amdgcn_sched_barrier(0)
; template <class Epi, class Sched, bool ALIGN_EPI = false, bool SP2 = false>
; __device__ __forceinline__ void gemm_phase(PG8_LAS unsigned char* lds, const Gemm g, const Sched& S, const Epi& E) {
;     ...
;             PG8_LDB(B0, 0, 0); PG8_LDB(B1, 0, 1); PG8_SCHED; PG8_LDA(At, 0, 0); PG8_STAGE(PG8_SA(1, 1), a1 + hstepA, voffA);
;             PG8_WAIT_V(8); PG8_WAIT_L(0); PG8_BAR; PG8_MMA(0, 0, At, B0); PG8_MMA(0, 1, At, B1); PG8_BAR; PG8_SCHED;
;             PG8_LDA(At, 0, 1); PG8_STAGE(PG8_SB(0, 0), b2, voffB); PG8_STAGE(PG8_SB(0, 1), b2 + hstepB, voffB); PG8_STAGE(PG8_SA(0, 0), a2, voffA);
;             PG8_WAIT_V(8); PG8_WAIT_L(0); PG8_BAR; PG8_MMA(1, 0, At, B0); PG8_MMA(1, 1, At, B1); PG8_BAR; PG8_SCHED;
;             PG8_LDB(B0, 1, 0); PG8_LDB(B1, 1, 1); PG8_SCHED; PG8_LDA(At, 1, 0); PG8_STAGE(PG8_SA(0, 1), a2 + hstepA, voffA);
;             PG8_WAIT_V(8); PG8_WAIT_L(0); PG8_BAR; PG8_MMA(0, 0, At, B0); PG8_MMA(0, 1, At, B1); PG8_BAR; PG8_SCHED;
.LBB0_995:
	v_add_u32_e32 v154, s38, v175
	v_add_u32_e32 v170, s41, v175
	ds_read_b128 v[142:145], v154
	ds_read_b128 v[146:149], v154 offset:1024
	ds_read_b128 v[150:153], v154 offset:2048
	ds_read_b128 v[154:157], v154 offset:3072
	ds_read_b128 v[158:161], v170
	ds_read_b128 v[162:165], v170 offset:1024
	ds_read_b128 v[166:169], v170 offset:2048
	ds_read_b128 v[170:173], v170 offset:3072
	s_add_u32 s2, s26, 0xfffc0080
	s_addc_u32 s28, s27, -1
	s_cmp_eq_u32 s82, 12
	s_cselect_b32 s31, s17, s28
	s_cselect_b32 s30, s23, s2
	s_cselect_b32 s29, s15, s79
	s_cselect_b32 s28, s25, s78
	v_lshl_add_u64 v[246:247], s[26:27], 0, v[140:141]
	s_add_i32 m0, s44, 0xc000
	ds_read_b128 v[208:211], v207
	ds_read_b128 v[218:221], v207 offset:1024
	ds_read_b128 v[222:225], v207 offset:2048
	ds_read_b128 v[226:229], v207 offset:3072
	ds_read_b128 v[230:233], v207 offset:4096
	ds_read_b128 v[234:237], v207 offset:5120
	ds_read_b128 v[238:241], v207 offset:6144
	ds_read_b128 v[242:245], v207 offset:7168
	global_load_lds_dwordx4 v[246:247], off
	v_lshl_add_u64 v[246:247], s[26:27], 0, v[138:139]
	s_add_i32 m0, s44, 0xe000
	s_nop 0
	global_load_lds_dwordx4 v[246:247], off
	s_waitcnt vmcnt(8)
	s_waitcnt lgkmcnt(0)
	s_barrier
	s_setprio 1
	s_waitcnt lgkmcnt(0)
	v_mfma_f32_16x16x32_bf16 v[124:127], v[142:145], v[208:211], v[124:127]
	v_mfma_f32_16x16x32_bf16 v[120:123], v[150:153], v[208:211], v[120:123]
	v_mfma_f32_16x16x32_bf16 v[108:111], v[142:145], v[222:225], v[108:111]
	v_mfma_f32_16x16x32_bf16 v[104:107], v[150:153], v[222:225], v[104:107]
	v_mfma_f32_16x16x32_bf16 v[92:95], v[142:145], v[230:233], v[92:95]
	v_mfma_f32_16x16x32_bf16 v[88:91], v[150:153], v[230:233], v[88:91]
	v_mfma_f32_16x16x32_bf16 v[76:79], v[142:145], v[238:241], v[76:79]
	v_mfma_f32_16x16x32_bf16 v[72:75], v[150:153], v[238:241], v[72:75]
	v_mfma_f32_16x16x32_bf16 v[124:127], v[146:149], v[218:221], v[124:127]
	v_mfma_f32_16x16x32_bf16 v[120:123], v[154:157], v[218:221], v[120:123]
	v_mfma_f32_16x16x32_bf16 v[108:111], v[146:149], v[226:229], v[108:111]
	v_mfma_f32_16x16x32_bf16 v[104:107], v[154:157], v[226:229], v[104:107]
	v_mfma_f32_16x16x32_bf16 v[92:95], v[146:149], v[234:237], v[92:95]
	v_mfma_f32_16x16x32_bf16 v[88:91], v[154:157], v[234:237], v[88:91]
	v_mfma_f32_16x16x32_bf16 v[76:79], v[146:149], v[242:245], v[76:79]
	v_mfma_f32_16x16x32_bf16 v[72:75], v[154:157], v[242:245], v[72:75]
	s_setprio 0
	s_setprio 1
	v_mfma_f32_16x16x32_bf16 v[116:119], v[158:161], v[208:211], v[116:119]
	v_mfma_f32_16x16x32_bf16 v[112:115], v[166:169], v[208:211], v[112:115]
	v_mfma_f32_16x16x32_bf16 v[100:103], v[158:161], v[222:225], v[100:103]
	v_mfma_f32_16x16x32_bf16 v[96:99], v[166:169], v[222:225], v[96:99]
	v_mfma_f32_16x16x32_bf16 v[84:87], v[158:161], v[230:233], v[84:87]
	v_mfma_f32_16x16x32_bf16 v[80:83], v[166:169], v[230:233], v[80:83]
	v_mfma_f32_16x16x32_bf16 v[68:71], v[158:161], v[238:241], v[68:71]
	v_mfma_f32_16x16x32_bf16 v[64:67], v[166:169], v[238:241], v[64:67]
	v_mfma_f32_16x16x32_bf16 v[116:119], v[162:165], v[218:221], v[116:119]
	v_mfma_f32_16x16x32_bf16 v[112:115], v[170:173], v[218:221], v[112:115]
	v_mfma_f32_16x16x32_bf16 v[100:103], v[162:165], v[226:229], v[100:103]
	v_mfma_f32_16x16x32_bf16 v[96:99], v[170:173], v[226:229], v[96:99]
	v_mfma_f32_16x16x32_bf16 v[84:87], v[162:165], v[234:237], v[84:87]
	v_mfma_f32_16x16x32_bf16 v[80:83], v[170:173], v[234:237], v[80:83]
	v_mfma_f32_16x16x32_bf16 v[68:71], v[162:165], v[242:245], v[68:71]
	v_mfma_f32_16x16x32_bf16 v[64:67], v[170:173], v[242:245], v[64:67]
	s_setprio 0
	s_barrier
	s_mov_b32 m0, s39
	v_lshl_add_u64 v[246:247], s[28:29], 0, v[130:131]
	s_add_u32 s84, s28, 0x40000
	ds_read_b128 v[208:211], v207 offset:16384
	ds_read_b128 v[218:221], v207 offset:17408
	ds_read_b128 v[222:225], v207 offset:18432
	ds_read_b128 v[226:229], v207 offset:19456
	ds_read_b128 v[230:233], v207 offset:20480
	ds_read_b128 v[234:237], v207 offset:21504
	ds_read_b128 v[238:241], v207 offset:22528
	ds_read_b128 v[242:245], v207 offset:23552
	global_load_lds_dwordx4 v[246:247], off
	v_lshl_add_u64 v[248:249], s[28:29], 0, v[134:135]
	s_mov_b32 m0, s40
	s_addc_u32 s85, s29, 0
	global_load_lds_dwordx4 v[248:249], off
	v_lshl_add_u64 v[250:251], s[84:85], 0, v[130:131]
	s_mov_b32 m0, s42
	v_lshl_add_u64 v[252:253], s[30:31], 0, v[132:133]
	global_load_lds_dwordx4 v[250:251], off
	v_lshl_add_u64 v[250:251], s[84:85], 0, v[134:135]
	s_mov_b32 m0, s43
	s_nop 0
	global_load_lds_dwordx4 v[250:251], off
	v_lshl_add_u64 v[250:251], s[30:31], 0, v[128:129]
	s_mov_b32 m0, s44
	s_nop 0
	global_load_lds_dwordx4 v[250:251], off
	s_mov_b32 m0, s45
	s_nop 0
	global_load_lds_dwordx4 v[252:253], off
	s_waitcnt vmcnt(8)
	s_waitcnt lgkmcnt(0)
	s_barrier
; #define PG8_STAGE(bufoff, gbase, voff) do { _Pragma("unroll") for (int _i = 0; _i < 2; ++_i) \
;         __builtin_amdgcn_global_load_lds((const unsigned*)((const char*)(gbase) + (voff)[_i]), (PG8_LAS unsigned*)(lds + (bufoff) + ldsw + _i * 8192), 16, 0, 0); } while (0)
; #define PG8_LDA(dst, b, h) do { _Pragma("unroll") for (int m = 0; m < 4; ++m) _Pragma("unroll") for (int k = 0; k < 2; ++k) dst[m][k] = *(const PG8_LAS bf16x8*)(lds + PG8_SA(b, h) + aoff + m * 2048 + k * 1024); } while (0)
; #define PG8_LDB(dst, b, h) do { _Pragma("unroll") for (int n = 0; n < 2; ++n) _Pragma("unroll") for (int k = 0; k < 2; ++k) dst[n][k] = *(const PG8_LAS bf16x8*)(lds + PG8_SB(b, h) + boff + n * 2048 + k * 1024); } while (0)
; #define PG8_MMA(ai, bj, At, Bt) do { __builtin_amdgcn_s_setprio(1); _Pragma("unroll") for (int m = 0; m < 4; ++m) _Pragma("unroll") for (int n = 0; n < 2; ++n) _Pragma("unroll") for (int k = 0; k < 2; ++k) \
;         acc[ai][bj][m][n] = __builtin_amdgcn_mfma_f32_16x16x32_bf16(Bt[n][k], At[m][k], acc[ai][bj][m][n], 0, 0, 0); __builtin_amdgcn_s_setprio(0); } while (0)
; #define PG8_WAIT_V(n) asm volatile("s_waitcnt vmcnt(" #n ")" ::: "memory")
; #define PG8_WAIT_L(n) asm volatile("s_waitcnt lgkmcnt(" #n ")" ::: "memory")
; #define PG8_BAR __builtin_amdgcn_s_barrier()
; #define PG8_SCHED __builtin_amdgcn_sched_barrier(0)
; template <class Epi, class Sched, bool ALIGN_EPI = false, bool SP2 = false>
; __device__ __forceinline__ void gemm_phase(PG8_LAS unsigned char* lds, const Gemm g, const Sched& S, const Epi& E) {
;     ...
;             PG8_WAIT_V(8); PG8_WAIT_L(0); PG8_BAR; PG8_MMA(1, 0, At, B0); PG8_MMA(1, 1, At, B1); PG8_BAR; PG8_SCHED;
;             PG8_LDB(B0, 1, 0); PG8_LDB(B1, 1, 1); PG8_SCHED; PG8_LDA(At, 1, 0); PG8_STAGE(PG8_SA(0, 1), a2 + hstepA, voffA);
;             PG8_WAIT_V(8); PG8_WAIT_L(0); PG8_BAR; PG8_MMA(0, 0, At, B0); PG8_MMA(0, 1, At, B1); PG8_BAR; PG8_SCHED;
	s_setprio 1
	s_waitcnt lgkmcnt(0)
	v_mfma_f32_16x16x32_bf16 v[60:63], v[142:145], v[208:211], v[60:63]
	v_mfma_f32_16x16x32_bf16 v[56:59], v[150:153], v[208:211], v[56:59]
	v_mfma_f32_16x16x32_bf16 v[44:47], v[142:145], v[222:225], v[44:47]
	v_mfma_f32_16x16x32_bf16 v[40:43], v[150:153], v[222:225], v[40:43]
	v_mfma_f32_16x16x32_bf16 v[28:31], v[142:145], v[230:233], v[28:31]
	v_mfma_f32_16x16x32_bf16 v[24:27], v[150:153], v[230:233], v[24:27]
	v_mfma_f32_16x16x32_bf16 v[12:15], v[142:145], v[238:241], v[12:15]
	v_mfma_f32_16x16x32_bf16 v[8:11], v[150:153], v[238:241], v[8:11]
	v_mfma_f32_16x16x32_bf16 v[60:63], v[146:149], v[218:221], v[60:63]
	v_mfma_f32_16x16x32_bf16 v[56:59], v[154:157], v[218:221], v[56:59]
	v_mfma_f32_16x16x32_bf16 v[44:47], v[146:149], v[226:229], v[44:47]
	v_mfma_f32_16x16x32_bf16 v[40:43], v[154:157], v[226:229], v[40:43]
	v_mfma_f32_16x16x32_bf16 v[28:31], v[146:149], v[234:237], v[28:31]
	v_mfma_f32_16x16x32_bf16 v[24:27], v[154:157], v[234:237], v[24:27]
	v_mfma_f32_16x16x32_bf16 v[12:15], v[146:149], v[242:245], v[12:15]
	v_mfma_f32_16x16x32_bf16 v[8:11], v[154:157], v[242:245], v[8:11]
	s_setprio 0
	s_setprio 1
	v_mfma_f32_16x16x32_bf16 v[52:55], v[158:161], v[208:211], v[52:55]
	v_mfma_f32_16x16x32_bf16 v[48:51], v[166:169], v[208:211], v[48:51]
	v_mfma_f32_16x16x32_bf16 v[36:39], v[158:161], v[222:225], v[36:39]
	v_mfma_f32_16x16x32_bf16 v[32:35], v[166:169], v[222:225], v[32:35]
	v_mfma_f32_16x16x32_bf16 v[20:23], v[158:161], v[230:233], v[20:23]
	v_mfma_f32_16x16x32_bf16 v[16:19], v[166:169], v[230:233], v[16:19]
	v_mfma_f32_16x16x32_bf16 v[4:7], v[158:161], v[238:241], v[4:7]
	v_mfma_f32_16x16x32_bf16 v[0:3], v[166:169], v[238:241], v[0:3]
	v_mfma_f32_16x16x32_bf16 v[52:55], v[162:165], v[218:221], v[52:55]
	v_mfma_f32_16x16x32_bf16 v[48:51], v[170:173], v[218:221], v[48:51]
	v_mfma_f32_16x16x32_bf16 v[36:39], v[162:165], v[226:229], v[36:39]
	v_mfma_f32_16x16x32_bf16 v[32:35], v[170:173], v[226:229], v[32:35]
	v_mfma_f32_16x16x32_bf16 v[20:23], v[162:165], v[234:237], v[20:23]
	v_mfma_f32_16x16x32_bf16 v[16:19], v[170:173], v[234:237], v[16:19]
	v_mfma_f32_16x16x32_bf16 v[4:7], v[162:165], v[242:245], v[4:7]
	v_mfma_f32_16x16x32_bf16 v[0:3], v[170:173], v[242:245], v[0:3]
	s_setprio 0
	s_barrier
	v_add_u32_e32 v154, s50, v175
	v_add_u32_e32 v170, s65, v175
	ds_read_b128 v[142:145], v154
	ds_read_b128 v[146:149], v154 offset:1024
	ds_read_b128 v[150:153], v154 offset:2048
	ds_read_b128 v[154:157], v154 offset:3072
	ds_read_b128 v[158:161], v170
	ds_read_b128 v[162:165], v170 offset:1024
	ds_read_b128 v[166:169], v170 offset:2048
	ds_read_b128 v[170:173], v170 offset:3072
	s_add_u32 s30, s30, 0x40000
	s_addc_u32 s31, s31, 0
	s_mov_b32 m0, s48
	v_lshl_add_u64 v[194:195], s[30:31], 0, v[128:129]
	ds_read_b128 v[208:211], v207 offset:32768
	ds_read_b128 v[218:221], v207 offset:33792
	ds_read_b128 v[222:225], v207 offset:34816
	ds_read_b128 v[226:229], v207 offset:35840
	ds_read_b128 v[230:233], v207 offset:36864
	ds_read_b128 v[234:237], v207 offset:37888
	ds_read_b128 v[238:241], v207 offset:38912
	ds_read_b128 v[242:245], v207 offset:39936
	global_load_lds_dwordx4 v[194:195], off
	v_lshl_add_u64 v[194:195], s[30:31], 0, v[132:133]
	s_mov_b32 m0, s49
	s_nop 0
	global_load_lds_dwordx4 v[194:195], off
	s_waitcnt vmcnt(8)
	s_waitcnt lgkmcnt(0)
	s_barrier
	s_setprio 1
	s_waitcnt lgkmcnt(0)
	v_mfma_f32_16x16x32_bf16 v[124:127], v[142:145], v[208:211], v[124:127]
	v_mfma_f32_16x16x32_bf16 v[120:123], v[150:153], v[208:211], v[120:123]
	v_mfma_f32_16x16x32_bf16 v[108:111], v[142:145], v[222:225], v[108:111]
	v_mfma_f32_16x16x32_bf16 v[104:107], v[150:153], v[222:225], v[104:107]
	v_mfma_f32_16x16x32_bf16 v[92:95], v[142:145], v[230:233], v[92:95]
	v_mfma_f32_16x16x32_bf16 v[88:91], v[150:153], v[230:233], v[88:91]
	v_mfma_f32_16x16x32_bf16 v[76:79], v[142:145], v[238:241], v[76:79]
	v_mfma_f32_16x16x32_bf16 v[72:75], v[150:153], v[238:241], v[72:75]
	v_mfma_f32_16x16x32_bf16 v[124:127], v[146:149], v[218:221], v[124:127]
	v_mfma_f32_16x16x32_bf16 v[120:123], v[154:157], v[218:221], v[120:123]
	v_mfma_f32_16x16x32_bf16 v[108:111], v[146:149], v[226:229], v[108:111]
	v_mfma_f32_16x16x32_bf16 v[104:107], v[154:157], v[226:229], v[104:107]
	v_mfma_f32_16x16x32_bf16 v[92:95], v[146:149], v[234:237], v[92:95]
	v_mfma_f32_16x16x32_bf16 v[88:91], v[154:157], v[234:237], v[88:91]
	v_mfma_f32_16x16x32_bf16 v[76:79], v[146:149], v[242:245], v[76:79]
	v_mfma_f32_16x16x32_bf16 v[72:75], v[154:157], v[242:245], v[72:75]
	s_setprio 0
	s_setprio 1
	v_mfma_f32_16x16x32_bf16 v[116:119], v[158:161], v[208:211], v[116:119]
	v_mfma_f32_16x16x32_bf16 v[112:115], v[166:169], v[208:211], v[112:115]
	v_mfma_f32_16x16x32_bf16 v[100:103], v[158:161], v[222:225], v[100:103]
	v_mfma_f32_16x16x32_bf16 v[96:99], v[166:169], v[222:225], v[96:99]
	v_mfma_f32_16x16x32_bf16 v[84:87], v[158:161], v[230:233], v[84:87]
	v_mfma_f32_16x16x32_bf16 v[80:83], v[166:169], v[230:233], v[80:83]
	v_mfma_f32_16x16x32_bf16 v[68:71], v[158:161], v[238:241], v[68:71]
	v_mfma_f32_16x16x32_bf16 v[64:67], v[166:169], v[238:241], v[64:67]
	v_mfma_f32_16x16x32_bf16 v[116:119], v[162:165], v[218:221], v[116:119]
	v_mfma_f32_16x16x32_bf16 v[112:115], v[170:173], v[218:221], v[112:115]
	v_mfma_f32_16x16x32_bf16 v[100:103], v[162:165], v[226:229], v[100:103]
	v_mfma_f32_16x16x32_bf16 v[96:99], v[170:173], v[226:229], v[96:99]
	v_mfma_f32_16x16x32_bf16 v[84:87], v[162:165], v[234:237], v[84:87]
	v_mfma_f32_16x16x32_bf16 v[80:83], v[170:173], v[234:237], v[80:83]
	v_mfma_f32_16x16x32_bf16 v[68:71], v[162:165], v[242:245], v[68:71]
	v_mfma_f32_16x16x32_bf16 v[64:67], v[170:173], v[242:245], v[64:67]
	s_setprio 0
	s_barrier
; #define PG8_LDA(dst, b, h) do { _Pragma("unroll") for (int m = 0; m < 4; ++m) _Pragma("unroll") for (int k = 0; k < 2; ++k) dst[m][k] = *(const PG8_LAS bf16x8*)(lds + PG8_SA(b, h) + aoff + m * 2048 + k * 1024); } while (0)
; template <class Epi, class Sched, bool ALIGN_EPI = false, bool SP2 = false>
; __device__ __forceinline__ void gemm_phase(PG8_LAS unsigned char* lds, const Gemm g, const Sched& S, const Epi& E) {
;     ...
;             PG8_LDA(At, 1, 1); PG8_STAGE(PG8_SB(1, 0), b3, voffB); PG8_STAGE(PG8_SB(1, 1), b3 + hstepB, voffB); PG8_STAGE(PG8_SA(1, 0), a3, voffA);
;             PG8_WAIT_V(8); PG8_WAIT_L(0); PG8_BAR; PG8_MMA(1, 0, At, B0); PG8_MMA(1, 1, At, B1); PG8_BAR; PG8_SCHED;
;             } else {
;             PG8_LDB(B0, 0, 0); PG8_SCHED; PG8_LDA(At, 0, 0); PG8_STAGE(PG8_SA(1, 1), a1 + hstepA, voffA);
;             PG8_WAIT_L(8); PG8_BAR; PG8_WAIT_L(0); PG8_MMA(0, 0, At, B0); PG8_BAR; PG8_SCHED;
;             PG8_LDB(B1, 0, 1); PG8_STAGE(PG8_SB(0, 0), b2, voffB);
;             PG8_BAR; PG8_WAIT_L(0); PG8_MMA(0, 1, At, B1); PG8_BAR;
;             PG8_LDA(At, 0, 1); PG8_STAGE(PG8_SA(0, 0), a2, voffA);
;             PG8_BAR; PG8_WAIT_L(0); PG8_MMA(1, 0, At, B0); PG8_BAR; PG8_SCHED;
;             PG8_STAGE(PG8_SB(0, 1), b2 + hstepB, voffB);
;             PG8_WAIT_V(6); PG8_BAR; PG8_MMA(1, 1, At, B1); PG8_BAR;
;             PG8_LDB(B0, 1, 0); PG8_SCHED; PG8_LDA(At, 1, 0); PG8_STAGE(PG8_SA(0, 1), a2 + hstepA, voffA);
;             PG8_WAIT_L(8); PG8_BAR; PG8_WAIT_L(0); PG8_MMA(0, 0, At, B0); PG8_BAR; PG8_SCHED;
;             PG8_LDB(B1, 1, 1); PG8_STAGE(PG8_SB(1, 0), b3, voffB);
;             PG8_BAR; PG8_WAIT_L(0); PG8_MMA(0, 1, At, B1); PG8_BAR;
;             PG8_LDA(At, 1, 1); PG8_STAGE(PG8_SA(1, 0), a3, voffA);
;             PG8_BAR; PG8_WAIT_L(0); PG8_MMA(1, 0, At, B0); PG8_BAR; PG8_SCHED;
;             PG8_STAGE(PG8_SB(1, 1), b3 + hstepB, voffB);
;             PG8_WAIT_V(6); PG8_BAR; PG8_MMA(1, 1, At, B1); PG8_BAR;
;             }
;         }
;         if constexpr (ALIGN_EPI) { if (wr == 0) PG8_BAR; }
; __device__ __forceinline__ float row_rstd(const float* ssq, int row, int fq) {
;     const f32x4 v = *(const f32x4*)(ssq + (size_t)row * 16 + fq * 4);
;     float s = (v[0] + v[1]) + (v[2] + v[3]);
;     s += __shfl_xor(s, 16); s += __shfl_xor(s, 32);
;     return __builtin_amdgcn_rsqf(s * (1.f / DM) + EPS);
; }
	s_mov_b32 m0, s51
	v_lshl_add_u64 v[194:195], v[246:247], 0, s[76:77]
	s_add_u32 s28, s28, 0x40080
	ds_read_b128 v[208:211], v207 offset:49152
	ds_read_b128 v[218:221], v207 offset:50176
	ds_read_b128 v[222:225], v207 offset:51200
	ds_read_b128 v[226:229], v207 offset:52224
	ds_read_b128 v[230:233], v207 offset:53248
	ds_read_b128 v[234:237], v207 offset:54272
	ds_read_b128 v[238:241], v207 offset:55296
	ds_read_b128 v[242:245], v207 offset:56320
	global_load_lds_dwordx4 v[194:195], off
	v_lshl_add_u64 v[194:195], v[248:249], 0, s[76:77]
	s_mov_b32 m0, s60
	s_addc_u32 s29, s29, 0
	global_load_lds_dwordx4 v[194:195], off
	v_lshl_add_u64 v[194:195], s[28:29], 0, v[130:131]
	s_mov_b32 m0, s66
	s_nop 0
	global_load_lds_dwordx4 v[194:195], off
	v_lshl_add_u64 v[194:195], s[28:29], 0, v[134:135]
	s_mov_b32 m0, s67
	s_nop 0
	global_load_lds_dwordx4 v[194:195], off
	v_lshl_add_u64 v[194:195], v[250:251], 0, s[76:77]
	s_mov_b32 m0, s61
	s_nop 0
	global_load_lds_dwordx4 v[194:195], off
	v_lshl_add_u64 v[194:195], v[252:253], 0, s[76:77]
	s_mov_b32 m0, s64
	s_nop 0
	global_load_lds_dwordx4 v[194:195], off
	s_waitcnt vmcnt(8)
	s_waitcnt lgkmcnt(0)
	s_barrier
	s_setprio 1
	s_waitcnt lgkmcnt(0)
	v_mfma_f32_16x16x32_bf16 v[60:63], v[142:145], v[208:211], v[60:63]
	v_mfma_f32_16x16x32_bf16 v[56:59], v[150:153], v[208:211], v[56:59]
	v_mfma_f32_16x16x32_bf16 v[44:47], v[142:145], v[222:225], v[44:47]
	v_mfma_f32_16x16x32_bf16 v[40:43], v[150:153], v[222:225], v[40:43]
	v_mfma_f32_16x16x32_bf16 v[28:31], v[142:145], v[230:233], v[28:31]
	v_mfma_f32_16x16x32_bf16 v[24:27], v[150:153], v[230:233], v[24:27]
	v_mfma_f32_16x16x32_bf16 v[12:15], v[142:145], v[238:241], v[12:15]
	v_mfma_f32_16x16x32_bf16 v[8:11], v[150:153], v[238:241], v[8:11]
	v_mfma_f32_16x16x32_bf16 v[60:63], v[146:149], v[218:221], v[60:63]
	v_mfma_f32_16x16x32_bf16 v[56:59], v[154:157], v[218:221], v[56:59]
	v_mfma_f32_16x16x32_bf16 v[44:47], v[146:149], v[226:229], v[44:47]
	v_mfma_f32_16x16x32_bf16 v[40:43], v[154:157], v[226:229], v[40:43]
	v_mfma_f32_16x16x32_bf16 v[28:31], v[146:149], v[234:237], v[28:31]
	v_mfma_f32_16x16x32_bf16 v[24:27], v[154:157], v[234:237], v[24:27]
	v_mfma_f32_16x16x32_bf16 v[12:15], v[146:149], v[242:245], v[12:15]
	v_mfma_f32_16x16x32_bf16 v[8:11], v[154:157], v[242:245], v[8:11]
	s_setprio 0
	s_setprio 1
	v_mfma_f32_16x16x32_bf16 v[52:55], v[158:161], v[208:211], v[52:55]
	v_mfma_f32_16x16x32_bf16 v[48:51], v[166:169], v[208:211], v[48:51]
	v_mfma_f32_16x16x32_bf16 v[36:39], v[158:161], v[222:225], v[36:39]
	v_mfma_f32_16x16x32_bf16 v[32:35], v[166:169], v[222:225], v[32:35]
	v_mfma_f32_16x16x32_bf16 v[20:23], v[158:161], v[230:233], v[20:23]
	v_mfma_f32_16x16x32_bf16 v[16:19], v[166:169], v[230:233], v[16:19]
	v_mfma_f32_16x16x32_bf16 v[4:7], v[158:161], v[238:241], v[4:7]
	v_mfma_f32_16x16x32_bf16 v[0:3], v[166:169], v[238:241], v[0:3]
	v_mfma_f32_16x16x32_bf16 v[52:55], v[162:165], v[218:221], v[52:55]
	v_mfma_f32_16x16x32_bf16 v[48:51], v[170:173], v[218:221], v[48:51]
	v_mfma_f32_16x16x32_bf16 v[36:39], v[162:165], v[226:229], v[36:39]
	v_mfma_f32_16x16x32_bf16 v[32:35], v[170:173], v[226:229], v[32:35]
	v_mfma_f32_16x16x32_bf16 v[20:23], v[162:165], v[234:237], v[20:23]
	v_mfma_f32_16x16x32_bf16 v[16:19], v[170:173], v[234:237], v[16:19]
	v_mfma_f32_16x16x32_bf16 v[4:7], v[162:165], v[242:245], v[4:7]
	v_mfma_f32_16x16x32_bf16 v[0:3], v[170:173], v[242:245], v[0:3]
	s_setprio 0
	s_barrier
	s_add_i32 s82, s82, 2
	s_add_u32 s78, s78, 0x100
	s_addc_u32 s79, s79, 0
	s_add_u32 s26, s26, 0x100
	s_addc_u32 s27, s27, 0
	s_cmp_gt_u32 s82, 13
	s_cbranch_scc0 .LBB0_995
	v_lshl_add_u32 v228, s24, 8, v174
	v_mov_b32_e32 v144, v228
	v_ashrrev_i32_e32 v145, 31, v144
	v_lshlrev_b64 v[144:145], 6, v[144:145]
	v_lshl_add_u64 v[144:145], v[136:137], 0, v[144:145]
	global_load_dwordx4 v[144:147], v[144:145], off
	v_add_u32_e32 v148, 16, v228
	v_ashrrev_i32_e32 v149, 31, v148
	v_lshlrev_b64 v[148:149], 6, v[148:149]
	v_lshl_add_u64 v[148:149], v[136:137], 0, v[148:149]
	global_load_dwordx4 v[148:151], v[148:149], off
	v_add_u32_e32 v152, 32, v228
	v_ashrrev_i32_e32 v153, 31, v152
	v_lshlrev_b64 v[152:153], 6, v[152:153]
	v_lshl_add_u64 v[152:153], v[136:137], 0, v[152:153]
	global_load_dwordx4 v[152:155], v[152:153], off
	v_add_u32_e32 v156, 48, v228
	v_ashrrev_i32_e32 v157, 31, v156
	v_lshlrev_b64 v[156:157], 6, v[156:157]
	v_lshl_add_u64 v[156:157], v[136:137], 0, v[156:157]
	global_load_dwordx4 v[156:159], v[156:157], off
	v_add_u32_e32 v160, 0x80, v228
	v_ashrrev_i32_e32 v161, 31, v160
	v_lshlrev_b64 v[160:161], 6, v[160:161]
	v_lshl_add_u64 v[160:161], v[136:137], 0, v[160:161]
	global_load_dwordx4 v[160:163], v[160:161], off
	v_add_u32_e32 v164, 0x90, v228
	v_ashrrev_i32_e32 v165, 31, v164
	v_lshlrev_b64 v[164:165], 6, v[164:165]
	v_lshl_add_u64 v[164:165], v[136:137], 0, v[164:165]
	global_load_dwordx4 v[164:167], v[164:165], off
	v_add_u32_e32 v168, 0xa0, v228
	v_ashrrev_i32_e32 v169, 31, v168
	v_lshlrev_b64 v[168:169], 6, v[168:169]
	v_lshl_add_u64 v[168:169], v[136:137], 0, v[168:169]
	global_load_dwordx4 v[168:171], v[168:169], off
	v_add_u32_e32 v222, 0xb0, v228
	v_ashrrev_i32_e32 v223, 31, v222
	v_lshlrev_b64 v[222:223], 6, v[222:223]
	v_lshl_add_u64 v[222:223], v[136:137], 0, v[222:223]
	global_load_dwordx4 v[222:225], v[222:223], off
	v_xor_b32_e32 v226, 16, v215
	v_xor_b32_e32 v227, 32, v215
	v_lshlrev_b32_e32 v226, 2, v226
	v_lshlrev_b32_e32 v227, 2, v227
	s_and_b64 vcc, exec, s[12:13]
	s_cbranch_vccz .LBB0_998
	s_barrier
; __device__ __forceinline__ float row_rstd(const float* ssq, int row, int fq) {
;     const f32x4 v = *(const f32x4*)(ssq + (size_t)row * 16 + fq * 4);
;     float s = (v[0] + v[1]) + (v[2] + v[3]);
;     s += __shfl_xor(s, 16); s += __shfl_xor(s, 32);
;     return __builtin_amdgcn_rsqf(s * (1.f / DM) + EPS);
; }
;     __device__ __forceinline__ void operator()(const f32x4 (&acc_)[2][2][4][2], const pg8::Unit& u, int wr, int wc, int fr, int fq) const {
;     ...
;         const int row0 = u.pm * 256 + wr * 64 + fr, lrow0 = wr * 64 + fr;
; #pragma unroll
;         for (int ai = 0; ai < 2; ++ai)
; #pragma unroll
;             for (int m = 0; m < 4; ++m) { const float rs = row_rstd(ssq, row0 + ai * 128 + m * 16, fq); float mx = -3.0e38f;
; #pragma unroll
;                 for (int bj = 0; bj < 2; ++bj)
; #pragma unroll
;                     for (int n = 0; n < 2; ++n) { const f32x4 a = acc[ai][bj][m][n]; mx = fmaxf(mx, fmaxf(fmaxf(a[0], a[1]), fmaxf(a[2], a[3]))); }
;                 mx *= rs; mx = fmaxf(mx, __shfl_xor(mx, 16)); mx = fmaxf(mx, __shfl_xor(mx, 32));
;                 if (fq == 0) xch[(lrow0 + ai * 128 + m * 16) * 4 + wc] = mx; }
.LBB0_998:
	s_waitcnt vmcnt(0)
	v_add_f32_e32 v144, v144, v145
	v_add_f32_e32 v146, v146, v147
	v_add_f32_e32 v148, v148, v149
	v_add_f32_e32 v150, v150, v151
	v_add_f32_e32 v152, v152, v153
	v_add_f32_e32 v154, v154, v155
	v_add_f32_e32 v156, v156, v157
	v_add_f32_e32 v158, v158, v159
	v_add_f32_e32 v160, v160, v161
	v_add_f32_e32 v162, v162, v163
	v_add_f32_e32 v164, v164, v165
	v_add_f32_e32 v166, v166, v167
	v_add_f32_e32 v168, v168, v169
	v_add_f32_e32 v170, v170, v171
	v_add_f32_e32 v222, v222, v223
	v_add_f32_e32 v224, v224, v225
	v_add_f32_e32 v144, v144, v146
	v_add_f32_e32 v148, v148, v150
	v_add_f32_e32 v152, v152, v154
	v_add_f32_e32 v156, v156, v158
	v_add_f32_e32 v160, v160, v162
	v_add_f32_e32 v164, v164, v166
	v_add_f32_e32 v168, v168, v170
	v_add_f32_e32 v222, v222, v224
	ds_bpermute_b32 v145, v226, v144
	ds_bpermute_b32 v149, v226, v148
	ds_bpermute_b32 v153, v226, v152
	ds_bpermute_b32 v157, v226, v156
	ds_bpermute_b32 v161, v226, v160
	ds_bpermute_b32 v165, v226, v164
	ds_bpermute_b32 v169, v226, v168
	ds_bpermute_b32 v223, v226, v222
	s_waitcnt lgkmcnt(0)
	v_add_f32_e32 v144, v144, v145
	v_add_f32_e32 v148, v148, v149
	v_add_f32_e32 v152, v152, v153
	v_add_f32_e32 v156, v156, v157
	v_add_f32_e32 v160, v160, v161
	v_add_f32_e32 v164, v164, v165
	v_add_f32_e32 v168, v168, v169
	v_add_f32_e32 v222, v222, v223
	ds_bpermute_b32 v145, v227, v144
	ds_bpermute_b32 v149, v227, v148
	ds_bpermute_b32 v153, v227, v152
	ds_bpermute_b32 v157, v227, v156
	ds_bpermute_b32 v161, v227, v160
	ds_bpermute_b32 v165, v227, v164
	ds_bpermute_b32 v169, v227, v168
	ds_bpermute_b32 v223, v227, v222
	s_waitcnt lgkmcnt(0)
	v_add_f32_e32 v144, v144, v145
	v_add_f32_e32 v148, v148, v149
	v_add_f32_e32 v152, v152, v153
	v_add_f32_e32 v156, v156, v157
	v_add_f32_e32 v160, v160, v161
	v_add_f32_e32 v164, v164, v165
	v_add_f32_e32 v168, v168, v169
	v_add_f32_e32 v222, v222, v223
	v_fmamk_f32 v144, v144, 0x3a800000, v212
	v_fmamk_f32 v148, v148, 0x3a800000, v212
	v_fmamk_f32 v152, v152, 0x3a800000, v212
	v_fmamk_f32 v156, v156, 0x3a800000, v212
	v_fmamk_f32 v160, v160, 0x3a800000, v212
	v_fmamk_f32 v164, v164, 0x3a800000, v212
	v_fmamk_f32 v168, v168, 0x3a800000, v212
	v_fmamk_f32 v222, v222, 0x3a800000, v212
	v_rsq_f32_e32 v246, v144
	v_rsq_f32_e32 v247, v148
	v_rsq_f32_e32 v248, v152
	v_rsq_f32_e32 v249, v156
	v_rsq_f32_e32 v250, v160
	v_rsq_f32_e32 v251, v164
	v_rsq_f32_e32 v252, v168
	v_rsq_f32_e32 v253, v222
	s_nop 0
	v_and_b32_e32 v144, 64, v215
	v_xor_b32_e32 v143, 16, v215
	v_add_u32_e32 v144, 64, v144
	v_cmp_lt_i32_e32 vcc, v143, v144
	v_lshl_add_u32 v142, s24, 8, v174
	s_mov_b32 s2, 0xff61b1e6
	v_cndmask_b32_e32 v143, v215, v143, vcc
	v_lshlrev_b32_e32 v209, 2, v143
	v_xor_b32_e32 v143, 32, v215
	v_cmp_lt_i32_e32 vcc, v143, v144
	v_max_f32_e32 v148, v114, v114
	v_add_u32_e32 v210, s74, v176
	v_cndmask_b32_e32 v143, v215, v143, vcc
	v_lshlrev_b32_e32 v208, 2, v143
	v_ashrrev_i32_e32 v143, 31, v142
	v_lshlrev_b64 v[144:145], 6, v[142:143]
	v_lshl_add_u64 v[158:159], v[136:137], 0, v[144:145]
	s_nop 0
	s_waitcnt lgkmcnt(0)
	s_nop 3
	v_max_f32_e32 v146, v126, v126
	v_max_f32_e32 v147, v122, v122
	s_waitcnt lgkmcnt(0)
	s_nop 1
	s_waitcnt lgkmcnt(0)
	s_nop 0
	v_max_f32_e32 v145, v127, v127
	v_max_f32_e32 v145, v146, v145
	v_max_f32_e32 v146, v123, v123
	v_max_f32_e32 v146, v147, v146
	v_max3_f32 v145, v124, v125, v145
	v_max3_f32 v146, v120, v121, v146
	s_nop 0
	v_max3_f32 v145, v145, s2, v146
	v_max_f32_e32 v146, v119, v119
	v_max_f32_e32 v147, v118, v118
	v_max_f32_e32 v146, v147, v146
	v_max_f32_e32 v147, v115, v115
	v_mov_b32_e32 v144, v246
	v_max_f32_e32 v147, v148, v147
	v_max3_f32 v146, v116, v117, v146
	v_max3_f32 v147, v112, v113, v147
	v_max3_f32 v145, v145, v146, v147
	v_mul_f32_e32 v144, v145, v144
	ds_bpermute_b32 v145, v209, v144
	s_waitcnt lgkmcnt(0)
	v_max_f32_e32 v145, v145, v145
	v_max_f32_e32 v144, v144, v145
	ds_bpermute_b32 v145, v208, v144
	s_and_saveexec_b64 s[24:25], s[4:5]
	s_cbranch_execz .LBB0_1000
	s_waitcnt lgkmcnt(0)
	v_max_f32_e32 v145, v145, v145
	v_max_f32_e32 v144, v144, v144
	v_max_f32_e32 v144, v144, v145
	ds_write_b32 v210, v144
